# v16: GEMM K loops: mid-segment s_setprio 0/1 toggles between the two 16-MFMA halves removed
# baseline (speedup 1.0000x reference)
; #define PG8_STAGE(bufoff, gbase, voff) do { _Pragma("unroll") for (int _i = 0; _i < 2; ++_i) \
;         __builtin_amdgcn_global_load_lds((const unsigned*)((const char*)(gbase) + (voff)[_i]), (PG8_LAS unsigned*)(lds + (bufoff) + ldsw + _i * 8192), 16, 0, 0); } while (0)
; #define PG8_LDA(dst, b, h) do { _Pragma("unroll") for (int m = 0; m < 4; ++m) _Pragma("unroll") for (int k = 0; k < 2; ++k) dst[m][k] = *(const PG8_LAS bf16x8*)(lds + PG8_SA(b, h) + aoff + m * 2048 + k * 1024); } while (0)
; #define PG8_LDB(dst, b, h) do { _Pragma("unroll") for (int n = 0; n < 2; ++n) _Pragma("unroll") for (int k = 0; k < 2; ++k) dst[n][k] = *(const PG8_LAS bf16x8*)(lds + PG8_SB(b, h) + boff + n * 2048 + k * 1024); } while (0)
; #define PG8_MMA(ai, bj, At, Bt) do { __builtin_amdgcn_s_setprio(1); _Pragma("unroll") for (int m = 0; m < 4; ++m) _Pragma("unroll") for (int n = 0; n < 2; ++n) _Pragma("unroll") for (int k = 0; k < 2; ++k) \
;         acc[ai][bj][m][n] = __builtin_amdgcn_mfma_f32_16x16x32_bf16(Bt[n][k], At[m][k], acc[ai][bj][m][n], 0, 0, 0); __builtin_amdgcn_s_setprio(0); } while (0)
; #define PG8_WAIT_V(n) asm volatile("s_waitcnt vmcnt(" #n ")" ::: "memory")
; #define PG8_BAR __builtin_amdgcn_s_barrier()
; template <class Epi, class Sched, bool ALIGN_EPI = false, bool SP2 = false>
; __device__ __forceinline__ void gemm_phase(PG8_LAS unsigned char* lds, const Gemm g, const Sched& S, const Epi& E, int tid_in) {
;     ...
;         for (int t = 0; t < nt; t += 2) {
;             const bool last = (t == nt - 2);
;             const char* a1 = cA + (size_t)(t + 1) * kstep;
;             const char* a2 = last ? nA : cA + (size_t)(t + 2) * kstep; const char* b2 = last ? nB : cB + (size_t)(t + 2) * kstep;
;             const char* a3 = a2 + kstep; const char* b3 = b2 + kstep;
;             if (last && has_next) S.a_ready(nxt);
;             if constexpr (SP2) {
;             PG8_LDB(B0, 0, 0); PG8_LDB(B1, 0, 1); PG8_SCHED; PG8_LDA(At, 0, 0); PG8_STAGE(PG8_SA(1, 1), a1 + hstepA, voffA);
;             PG8_WAIT_V(8); PG8_WAIT_L(0); PG8_BAR; PG8_MMA(0, 0, At, B0); PG8_MMA(0, 1, At, B1); PG8_BAR; PG8_SCHED;
;             PG8_LDA(At, 0, 1); PG8_STAGE(PG8_SB(0, 0), b2, voffB); PG8_STAGE(PG8_SB(0, 1), b2 + hstep, voffB); PG8_STAGE(PG8_SA(0, 0), a2, voffA);
;             PG8_WAIT_V(8); PG8_WAIT_L(0); PG8_BAR; PG8_MMA(1, 0, At, B0); PG8_MMA(1, 1, At, B1); PG8_BAR; PG8_SCHED;
.LBB0_108:
	s_add_i32 s62, s15, 2
	s_add_u32 s20, s18, 0x80
	s_addc_u32 s21, s19, 0
	s_add_i32 s63, 0, 0x10000
	s_cmp_eq_u32 s57, s15
	s_cselect_b32 s21, s39, s21
	s_cselect_b32 s20, s38, s20
	v_add_u32_e32 v146, s63, v145
	s_cselect_b32 s65, s45, s13
	s_cselect_b32 s64, s44, s12
	s_add_i32 s15, 0, 0x14000
	ds_read_b128 v[140:143], v146
	ds_read_b128 v[150:153], v146 offset:1024
	ds_read_b128 v[154:157], v146 offset:2048
	ds_read_b128 v[158:161], v146 offset:3072
	v_add_u32_e32 v146, s15, v145
	ds_read_b128 v[162:165], v146
	ds_read_b128 v[166:169], v146 offset:1024
	ds_read_b128 v[170:173], v146 offset:2048
	ds_read_b128 v[174:177], v146 offset:3072
	v_lshl_add_u64 v[146:147], s[18:19], 0, v[136:137]
	s_add_i32 m0, s50, 0xc000
	ds_read_b128 v[178:181], v149
	ds_read_b128 v[182:185], v149 offset:1024
	ds_read_b128 v[186:189], v149 offset:2048
	ds_read_b128 v[190:193], v149 offset:3072
	ds_read_b128 v[204:207], v149 offset:4096
	ds_read_b128 v[208:211], v149 offset:5120
	ds_read_b128 v[212:215], v149 offset:6144
	ds_read_b128 v[216:219], v149 offset:7168
	global_load_lds_dwordx4 v[146:147], off
	v_lshl_add_u64 v[146:147], s[18:19], 0, v[138:139]
	s_add_i32 m0, s50, 0xe000
	s_nop 0
	global_load_lds_dwordx4 v[146:147], off
	s_waitcnt vmcnt(8)
	s_waitcnt lgkmcnt(0)
	s_barrier
	s_setprio 1
	s_waitcnt lgkmcnt(0)
	v_mfma_f32_16x16x32_bf16 v[126:129], v[140:143], v[178:181], v[126:129]
	v_mfma_f32_16x16x32_bf16 v[122:125], v[154:157], v[178:181], v[122:125]
	v_mfma_f32_16x16x32_bf16 v[110:113], v[140:143], v[186:189], v[110:113]
	v_mfma_f32_16x16x32_bf16 v[106:109], v[154:157], v[186:189], v[106:109]
	v_mfma_f32_16x16x32_bf16 v[94:97], v[140:143], v[204:207], v[94:97]
	v_mfma_f32_16x16x32_bf16 v[90:93], v[154:157], v[204:207], v[90:93]
	v_mfma_f32_16x16x32_bf16 v[78:81], v[140:143], v[212:215], v[78:81]
	v_mfma_f32_16x16x32_bf16 v[74:77], v[154:157], v[212:215], v[74:77]
	v_mfma_f32_16x16x32_bf16 v[126:129], v[150:153], v[182:185], v[126:129]
	v_mfma_f32_16x16x32_bf16 v[122:125], v[158:161], v[182:185], v[122:125]
	v_mfma_f32_16x16x32_bf16 v[110:113], v[150:153], v[190:193], v[110:113]
	v_mfma_f32_16x16x32_bf16 v[106:109], v[158:161], v[190:193], v[106:109]
	v_mfma_f32_16x16x32_bf16 v[94:97], v[150:153], v[208:211], v[94:97]
	v_mfma_f32_16x16x32_bf16 v[90:93], v[158:161], v[208:211], v[90:93]
	v_mfma_f32_16x16x32_bf16 v[78:81], v[150:153], v[216:219], v[78:81]
	v_mfma_f32_16x16x32_bf16 v[74:77], v[158:161], v[216:219], v[74:77]
	v_mfma_f32_16x16x32_bf16 v[118:121], v[162:165], v[178:181], v[118:121]
	v_mfma_f32_16x16x32_bf16 v[114:117], v[170:173], v[178:181], v[114:117]
	v_mfma_f32_16x16x32_bf16 v[102:105], v[162:165], v[186:189], v[102:105]
	v_mfma_f32_16x16x32_bf16 v[98:101], v[170:173], v[186:189], v[98:101]
	v_mfma_f32_16x16x32_bf16 v[86:89], v[162:165], v[204:207], v[86:89]
	v_mfma_f32_16x16x32_bf16 v[82:85], v[170:173], v[204:207], v[82:85]
	v_mfma_f32_16x16x32_bf16 v[70:73], v[162:165], v[212:215], v[70:73]
	v_mfma_f32_16x16x32_bf16 v[66:69], v[170:173], v[212:215], v[66:69]
	v_mfma_f32_16x16x32_bf16 v[118:121], v[166:169], v[182:185], v[118:121]
	v_mfma_f32_16x16x32_bf16 v[114:117], v[174:177], v[182:185], v[114:117]
	v_mfma_f32_16x16x32_bf16 v[102:105], v[166:169], v[190:193], v[102:105]
	v_mfma_f32_16x16x32_bf16 v[98:101], v[174:177], v[190:193], v[98:101]
	v_mfma_f32_16x16x32_bf16 v[86:89], v[166:169], v[208:211], v[86:89]
	v_mfma_f32_16x16x32_bf16 v[82:85], v[174:177], v[208:211], v[82:85]
	v_mfma_f32_16x16x32_bf16 v[70:73], v[166:169], v[216:219], v[70:73]
	v_mfma_f32_16x16x32_bf16 v[66:69], v[174:177], v[216:219], v[66:69]
	s_setprio 0
	s_barrier
	s_add_i32 s63, s63, s49
	v_lshl_add_u64 v[146:147], s[64:65], 0, v[0:1]
	s_mov_b32 m0, s63
	ds_read_b128 v[178:181], v149 offset:16384
	ds_read_b128 v[182:185], v149 offset:17408
	ds_read_b128 v[186:189], v149 offset:18432
	ds_read_b128 v[190:193], v149 offset:19456
	ds_read_b128 v[204:207], v149 offset:20480
	ds_read_b128 v[208:211], v149 offset:21504
	ds_read_b128 v[212:215], v149 offset:22528
	ds_read_b128 v[216:219], v149 offset:23552
	global_load_lds_dwordx4 v[146:147], off
	s_add_i32 m0, s63, 0x2000
	v_lshl_add_u64 v[194:195], s[64:65], 0, v[130:131]
	s_add_u32 s64, s64, s0
	s_addc_u32 s65, s65, s1
	s_add_i32 s15, s15, s49
	global_load_lds_dwordx4 v[194:195], off
	v_lshl_add_u64 v[200:201], s[64:65], 0, v[0:1]
	s_mov_b32 m0, s15
	v_lshl_add_u64 v[220:221], s[64:65], 0, v[130:131]
	global_load_lds_dwordx4 v[200:201], off
	s_add_i32 m0, s15, 0x2000
	v_lshl_add_u64 v[222:223], s[20:21], 0, v[134:135]
	global_load_lds_dwordx4 v[220:221], off
	s_mov_b32 m0, s50
	v_lshl_add_u64 v[224:225], s[20:21], 0, v[132:133]
	global_load_lds_dwordx4 v[222:223], off
	s_mov_b32 m0, s51
	s_nop 0
	global_load_lds_dwordx4 v[224:225], off
	s_waitcnt vmcnt(8)
	s_waitcnt lgkmcnt(0)
	s_barrier
; #define PG8_STAGE(bufoff, gbase, voff) do { _Pragma("unroll") for (int _i = 0; _i < 2; ++_i) \
;         __builtin_amdgcn_global_load_lds((const unsigned*)((const char*)(gbase) + (voff)[_i]), (PG8_LAS unsigned*)(lds + (bufoff) + ldsw + _i * 8192), 16, 0, 0); } while (0)
; #define PG8_LDA(dst, b, h) do { _Pragma("unroll") for (int m = 0; m < 4; ++m) _Pragma("unroll") for (int k = 0; k < 2; ++k) dst[m][k] = *(const PG8_LAS bf16x8*)(lds + PG8_SA(b, h) + aoff + m * 2048 + k * 1024); } while (0)
; #define PG8_LDB(dst, b, h) do { _Pragma("unroll") for (int n = 0; n < 2; ++n) _Pragma("unroll") for (int k = 0; k < 2; ++k) dst[n][k] = *(const PG8_LAS bf16x8*)(lds + PG8_SB(b, h) + boff + n * 2048 + k * 1024); } while (0)
; #define PG8_MMA(ai, bj, At, Bt) do { __builtin_amdgcn_s_setprio(1); _Pragma("unroll") for (int m = 0; m < 4; ++m) _Pragma("unroll") for (int n = 0; n < 2; ++n) _Pragma("unroll") for (int k = 0; k < 2; ++k) \
;         acc[ai][bj][m][n] = __builtin_amdgcn_mfma_f32_16x16x32_bf16(Bt[n][k], At[m][k], acc[ai][bj][m][n], 0, 0, 0); __builtin_amdgcn_s_setprio(0); } while (0)
; #define PG8_WAIT_V(n) asm volatile("s_waitcnt vmcnt(" #n ")" ::: "memory")
; #define PG8_WAIT_L(n) asm volatile("s_waitcnt lgkmcnt(" #n ")" ::: "memory")
; #define PG8_BAR __builtin_amdgcn_s_barrier()
; #define PG8_SCHED __builtin_amdgcn_sched_barrier(0)
; template <class Epi, class Sched, bool ALIGN_EPI = false, bool SP2 = false>
; __device__ __forceinline__ void gemm_phase(PG8_LAS unsigned char* lds, const Gemm g, const Sched& S, const Epi& E, int tid_in) {
;     ...
;             PG8_WAIT_V(8); PG8_WAIT_L(0); PG8_BAR; PG8_MMA(1, 0, At, B0); PG8_MMA(1, 1, At, B1); PG8_BAR; PG8_SCHED;
;             PG8_LDB(B0, 1, 0); PG8_LDB(B1, 1, 1); PG8_SCHED; PG8_LDA(At, 1, 0); PG8_STAGE(PG8_SA(0, 1), a2 + hstepA, voffA);
;             PG8_WAIT_V(8); PG8_WAIT_L(0); PG8_BAR; PG8_MMA(0, 0, At, B0); PG8_MMA(0, 1, At, B1); PG8_BAR; PG8_SCHED;
	s_setprio 1
	s_waitcnt lgkmcnt(0)
	v_mfma_f32_16x16x32_bf16 v[62:65], v[140:143], v[178:181], v[62:65]
	v_mfma_f32_16x16x32_bf16 v[58:61], v[154:157], v[178:181], v[58:61]
	v_mfma_f32_16x16x32_bf16 v[46:49], v[140:143], v[186:189], v[46:49]
	v_mfma_f32_16x16x32_bf16 v[42:45], v[154:157], v[186:189], v[42:45]
	v_mfma_f32_16x16x32_bf16 v[30:33], v[140:143], v[204:207], v[30:33]
	v_mfma_f32_16x16x32_bf16 v[26:29], v[154:157], v[204:207], v[26:29]
	v_mfma_f32_16x16x32_bf16 v[14:17], v[140:143], v[212:215], v[14:17]
	v_mfma_f32_16x16x32_bf16 v[10:13], v[154:157], v[212:215], v[10:13]
	v_mfma_f32_16x16x32_bf16 v[62:65], v[150:153], v[182:185], v[62:65]
	v_mfma_f32_16x16x32_bf16 v[58:61], v[158:161], v[182:185], v[58:61]
	v_mfma_f32_16x16x32_bf16 v[46:49], v[150:153], v[190:193], v[46:49]
	v_mfma_f32_16x16x32_bf16 v[42:45], v[158:161], v[190:193], v[42:45]
	v_mfma_f32_16x16x32_bf16 v[30:33], v[150:153], v[208:211], v[30:33]
	v_mfma_f32_16x16x32_bf16 v[26:29], v[158:161], v[208:211], v[26:29]
	v_mfma_f32_16x16x32_bf16 v[14:17], v[150:153], v[216:219], v[14:17]
	v_mfma_f32_16x16x32_bf16 v[10:13], v[158:161], v[216:219], v[10:13]
	v_mfma_f32_16x16x32_bf16 v[54:57], v[162:165], v[178:181], v[54:57]
	v_mfma_f32_16x16x32_bf16 v[50:53], v[170:173], v[178:181], v[50:53]
	v_mfma_f32_16x16x32_bf16 v[38:41], v[162:165], v[186:189], v[38:41]
	v_mfma_f32_16x16x32_bf16 v[34:37], v[170:173], v[186:189], v[34:37]
	v_mfma_f32_16x16x32_bf16 v[22:25], v[162:165], v[204:207], v[22:25]
	v_mfma_f32_16x16x32_bf16 v[18:21], v[170:173], v[204:207], v[18:21]
	v_mfma_f32_16x16x32_bf16 v[6:9], v[162:165], v[212:215], v[6:9]
	v_mfma_f32_16x16x32_bf16 v[2:5], v[170:173], v[212:215], v[2:5]
	v_mfma_f32_16x16x32_bf16 v[54:57], v[166:169], v[182:185], v[54:57]
	v_mfma_f32_16x16x32_bf16 v[50:53], v[174:177], v[182:185], v[50:53]
	v_mfma_f32_16x16x32_bf16 v[38:41], v[166:169], v[190:193], v[38:41]
	v_mfma_f32_16x16x32_bf16 v[34:37], v[174:177], v[190:193], v[34:37]
	v_mfma_f32_16x16x32_bf16 v[22:25], v[166:169], v[208:211], v[22:25]
	v_mfma_f32_16x16x32_bf16 v[18:21], v[174:177], v[208:211], v[18:21]
	v_mfma_f32_16x16x32_bf16 v[6:9], v[166:169], v[216:219], v[6:9]
	v_mfma_f32_16x16x32_bf16 v[2:5], v[174:177], v[216:219], v[2:5]
	s_setprio 0
	s_barrier
	s_add_i32 s15, 0, 0x18000
	s_add_i32 s63, 0, 0x1c000
	v_add_u32_e32 v158, s15, v145
	v_add_u32_e32 v174, s63, v145
	ds_read_b128 v[140:143], v158
	ds_read_b128 v[150:153], v158 offset:1024
	ds_read_b128 v[154:157], v158 offset:2048
	ds_read_b128 v[158:161], v158 offset:3072
	ds_read_b128 v[162:165], v174
	ds_read_b128 v[166:169], v174 offset:1024
	ds_read_b128 v[170:173], v174 offset:2048
	ds_read_b128 v[174:177], v174 offset:3072
	s_add_u32 s20, s20, s0
	s_addc_u32 s21, s21, s1
	s_mov_b32 m0, s52
	v_lshl_add_u64 v[226:227], s[20:21], 0, v[134:135]
	ds_read_b128 v[178:181], v149 offset:32768
	ds_read_b128 v[182:185], v149 offset:33792
	ds_read_b128 v[186:189], v149 offset:34816
	ds_read_b128 v[190:193], v149 offset:35840
	ds_read_b128 v[204:207], v149 offset:36864
	ds_read_b128 v[208:211], v149 offset:37888
	ds_read_b128 v[212:215], v149 offset:38912
	ds_read_b128 v[216:219], v149 offset:39936
	global_load_lds_dwordx4 v[226:227], off
	v_lshl_add_u64 v[226:227], s[20:21], 0, v[132:133]
	s_mov_b32 m0, s53
	s_nop 0
	global_load_lds_dwordx4 v[226:227], off
	s_waitcnt vmcnt(8)
	s_waitcnt lgkmcnt(0)
	s_barrier
	s_setprio 1
	s_waitcnt lgkmcnt(0)
	v_mfma_f32_16x16x32_bf16 v[126:129], v[140:143], v[178:181], v[126:129]
	v_mfma_f32_16x16x32_bf16 v[122:125], v[154:157], v[178:181], v[122:125]
	v_mfma_f32_16x16x32_bf16 v[110:113], v[140:143], v[186:189], v[110:113]
	v_mfma_f32_16x16x32_bf16 v[106:109], v[154:157], v[186:189], v[106:109]
	v_mfma_f32_16x16x32_bf16 v[94:97], v[140:143], v[204:207], v[94:97]
	v_mfma_f32_16x16x32_bf16 v[90:93], v[154:157], v[204:207], v[90:93]
	v_mfma_f32_16x16x32_bf16 v[78:81], v[140:143], v[212:215], v[78:81]
	v_mfma_f32_16x16x32_bf16 v[74:77], v[154:157], v[212:215], v[74:77]
	v_mfma_f32_16x16x32_bf16 v[126:129], v[150:153], v[182:185], v[126:129]
	v_mfma_f32_16x16x32_bf16 v[122:125], v[158:161], v[182:185], v[122:125]
	v_mfma_f32_16x16x32_bf16 v[110:113], v[150:153], v[190:193], v[110:113]
	v_mfma_f32_16x16x32_bf16 v[106:109], v[158:161], v[190:193], v[106:109]
	v_mfma_f32_16x16x32_bf16 v[94:97], v[150:153], v[208:211], v[94:97]
	v_mfma_f32_16x16x32_bf16 v[90:93], v[158:161], v[208:211], v[90:93]
	v_mfma_f32_16x16x32_bf16 v[78:81], v[150:153], v[216:219], v[78:81]
	v_mfma_f32_16x16x32_bf16 v[74:77], v[158:161], v[216:219], v[74:77]
	v_mfma_f32_16x16x32_bf16 v[118:121], v[162:165], v[178:181], v[118:121]
	v_mfma_f32_16x16x32_bf16 v[114:117], v[170:173], v[178:181], v[114:117]
	v_mfma_f32_16x16x32_bf16 v[102:105], v[162:165], v[186:189], v[102:105]
	v_mfma_f32_16x16x32_bf16 v[98:101], v[170:173], v[186:189], v[98:101]
	v_mfma_f32_16x16x32_bf16 v[86:89], v[162:165], v[204:207], v[86:89]
	v_mfma_f32_16x16x32_bf16 v[82:85], v[170:173], v[204:207], v[82:85]
	v_mfma_f32_16x16x32_bf16 v[70:73], v[162:165], v[212:215], v[70:73]
	v_mfma_f32_16x16x32_bf16 v[66:69], v[170:173], v[212:215], v[66:69]
	v_mfma_f32_16x16x32_bf16 v[118:121], v[166:169], v[182:185], v[118:121]
	v_mfma_f32_16x16x32_bf16 v[114:117], v[174:177], v[182:185], v[114:117]
	v_mfma_f32_16x16x32_bf16 v[102:105], v[166:169], v[190:193], v[102:105]
	v_mfma_f32_16x16x32_bf16 v[98:101], v[174:177], v[190:193], v[98:101]
	v_mfma_f32_16x16x32_bf16 v[86:89], v[166:169], v[208:211], v[86:89]
	v_mfma_f32_16x16x32_bf16 v[82:85], v[174:177], v[208:211], v[82:85]
	v_mfma_f32_16x16x32_bf16 v[70:73], v[166:169], v[216:219], v[70:73]
	v_mfma_f32_16x16x32_bf16 v[66:69], v[174:177], v[216:219], v[66:69]
	s_setprio 0
	s_barrier
; #define PG8_STAGE(bufoff, gbase, voff) do { _Pragma("unroll") for (int _i = 0; _i < 2; ++_i) \
;         __builtin_amdgcn_global_load_lds((const unsigned*)((const char*)(gbase) + (voff)[_i]), (PG8_LAS unsigned*)(lds + (bufoff) + ldsw + _i * 8192), 16, 0, 0); } while (0)
; #define PG8_LDA(dst, b, h) do { _Pragma("unroll") for (int m = 0; m < 4; ++m) _Pragma("unroll") for (int k = 0; k < 2; ++k) dst[m][k] = *(const PG8_LAS bf16x8*)(lds + PG8_SA(b, h) + aoff + m * 2048 + k * 1024); } while (0)
; #define PG8_MMA(ai, bj, At, Bt) do { __builtin_amdgcn_s_setprio(1); _Pragma("unroll") for (int m = 0; m < 4; ++m) _Pragma("unroll") for (int n = 0; n < 2; ++n) _Pragma("unroll") for (int k = 0; k < 2; ++k) \
;         acc[ai][bj][m][n] = __builtin_amdgcn_mfma_f32_16x16x32_bf16(Bt[n][k], At[m][k], acc[ai][bj][m][n], 0, 0, 0); __builtin_amdgcn_s_setprio(0); } while (0)
; #define PG8_WAIT_V(n) asm volatile("s_waitcnt vmcnt(" #n ")" ::: "memory")
; #define PG8_WAIT_L(n) asm volatile("s_waitcnt lgkmcnt(" #n ")" ::: "memory")
; #define PG8_BAR __builtin_amdgcn_s_barrier()
; #define PG8_SCHED __builtin_amdgcn_sched_barrier(0)
; template <class Epi, class Sched, bool ALIGN_EPI = false, bool SP2 = false>
; __device__ __forceinline__ void gemm_phase(PG8_LAS unsigned char* lds, const Gemm g, const Sched& S, const Epi& E, int tid_in) {
;     ...
;             PG8_LDA(At, 1, 1); PG8_STAGE(PG8_SB(1, 0), b3, voffB); PG8_STAGE(PG8_SB(1, 1), b3 + hstep, voffB); PG8_STAGE(PG8_SA(1, 0), a3, voffA);
;             PG8_WAIT_V(8); PG8_WAIT_L(0); PG8_BAR; PG8_MMA(1, 0, At, B0); PG8_MMA(1, 1, At, B1); PG8_BAR; PG8_SCHED;
	s_add_i32 s15, s15, s49
	v_lshl_add_u64 v[146:147], v[146:147], 0, s[28:29]
	s_mov_b32 m0, s15
	ds_read_b128 v[178:181], v149 offset:49152
	ds_read_b128 v[182:185], v149 offset:50176
	ds_read_b128 v[186:189], v149 offset:51200
	ds_read_b128 v[190:193], v149 offset:52224
	ds_read_b128 v[204:207], v149 offset:53248
	ds_read_b128 v[208:211], v149 offset:54272
	ds_read_b128 v[212:215], v149 offset:55296
	ds_read_b128 v[216:219], v149 offset:56320
	global_load_lds_dwordx4 v[146:147], off
	v_lshl_add_u64 v[146:147], v[194:195], 0, s[28:29]
	s_add_i32 m0, s15, 0x2000
	s_add_i32 s15, s63, s49
	global_load_lds_dwordx4 v[146:147], off
	v_lshl_add_u64 v[146:147], v[200:201], 0, s[28:29]
	s_mov_b32 m0, s15
	s_nop 0
	global_load_lds_dwordx4 v[146:147], off
	v_lshl_add_u64 v[146:147], v[220:221], 0, s[28:29]
	s_add_i32 m0, s15, 0x2000
	s_nop 0
	global_load_lds_dwordx4 v[146:147], off
	v_lshl_add_u64 v[146:147], v[222:223], 0, s[28:29]
	s_mov_b32 m0, s54
	s_nop 0
	global_load_lds_dwordx4 v[146:147], off
	v_lshl_add_u64 v[146:147], v[224:225], 0, s[28:29]
	s_mov_b32 m0, s55
	s_nop 0
	global_load_lds_dwordx4 v[146:147], off
	s_waitcnt vmcnt(8)
	s_waitcnt lgkmcnt(0)
	s_barrier
	s_setprio 1
	s_waitcnt lgkmcnt(0)
	v_mfma_f32_16x16x32_bf16 v[62:65], v[140:143], v[178:181], v[62:65]
	v_mfma_f32_16x16x32_bf16 v[58:61], v[154:157], v[178:181], v[58:61]
	v_mfma_f32_16x16x32_bf16 v[46:49], v[140:143], v[186:189], v[46:49]
	v_mfma_f32_16x16x32_bf16 v[42:45], v[154:157], v[186:189], v[42:45]
	v_mfma_f32_16x16x32_bf16 v[30:33], v[140:143], v[204:207], v[30:33]
	v_mfma_f32_16x16x32_bf16 v[26:29], v[154:157], v[204:207], v[26:29]
	v_mfma_f32_16x16x32_bf16 v[14:17], v[140:143], v[212:215], v[14:17]
	v_mfma_f32_16x16x32_bf16 v[10:13], v[154:157], v[212:215], v[10:13]
	v_mfma_f32_16x16x32_bf16 v[62:65], v[150:153], v[182:185], v[62:65]
	v_mfma_f32_16x16x32_bf16 v[58:61], v[158:161], v[182:185], v[58:61]
	v_mfma_f32_16x16x32_bf16 v[46:49], v[150:153], v[190:193], v[46:49]
	v_mfma_f32_16x16x32_bf16 v[42:45], v[158:161], v[190:193], v[42:45]
	v_mfma_f32_16x16x32_bf16 v[30:33], v[150:153], v[208:211], v[30:33]
	v_mfma_f32_16x16x32_bf16 v[26:29], v[158:161], v[208:211], v[26:29]
	v_mfma_f32_16x16x32_bf16 v[14:17], v[150:153], v[216:219], v[14:17]
	v_mfma_f32_16x16x32_bf16 v[10:13], v[158:161], v[216:219], v[10:13]
	v_mfma_f32_16x16x32_bf16 v[54:57], v[162:165], v[178:181], v[54:57]
	v_mfma_f32_16x16x32_bf16 v[50:53], v[170:173], v[178:181], v[50:53]
	v_mfma_f32_16x16x32_bf16 v[38:41], v[162:165], v[186:189], v[38:41]
	v_mfma_f32_16x16x32_bf16 v[34:37], v[170:173], v[186:189], v[34:37]
	v_mfma_f32_16x16x32_bf16 v[22:25], v[162:165], v[204:207], v[22:25]
	v_mfma_f32_16x16x32_bf16 v[18:21], v[170:173], v[204:207], v[18:21]
	v_mfma_f32_16x16x32_bf16 v[6:9], v[162:165], v[212:215], v[6:9]
	v_mfma_f32_16x16x32_bf16 v[2:5], v[170:173], v[212:215], v[2:5]
	v_mfma_f32_16x16x32_bf16 v[54:57], v[166:169], v[182:185], v[54:57]
	v_mfma_f32_16x16x32_bf16 v[50:53], v[174:177], v[182:185], v[50:53]
	v_mfma_f32_16x16x32_bf16 v[38:41], v[166:169], v[190:193], v[38:41]
	v_mfma_f32_16x16x32_bf16 v[34:37], v[174:177], v[190:193], v[34:37]
	v_mfma_f32_16x16x32_bf16 v[22:25], v[166:169], v[208:211], v[22:25]
	v_mfma_f32_16x16x32_bf16 v[18:21], v[174:177], v[208:211], v[18:21]
	v_mfma_f32_16x16x32_bf16 v[6:9], v[166:169], v[216:219], v[6:9]
	v_mfma_f32_16x16x32_bf16 v[2:5], v[174:177], v[216:219], v[2:5]
	s_setprio 0
	s_barrier
	s_add_u32 s18, s18, 0x100
	s_addc_u32 s19, s19, 0
	s_add_u32 s12, s12, 0x100
	s_addc_u32 s13, s13, 0
	s_cmp_ge_i32 s62, s56
	s_mov_b32 s15, s62
	s_cbranch_scc0 .LBB0_108
	v_readlane_b32 s62, v254, 62
	v_readlane_b32 s63, v254, 63
	s_movk_i32 s64, 0x6000
	v_readlane_b32 s65, v255, 9

; #define PG8_STAGE(bufoff, gbase, voff) do { _Pragma("unroll") for (int _i = 0; _i < 2; ++_i) \
;         __builtin_amdgcn_global_load_lds((const unsigned*)((const char*)(gbase) + (voff)[_i]), (PG8_LAS unsigned*)(lds + (bufoff) + ldsw + _i * 8192), 16, 0, 0); } while (0)
; #define PG8_LDA(dst, b, h) do { _Pragma("unroll") for (int m = 0; m < 4; ++m) _Pragma("unroll") for (int k = 0; k < 2; ++k) dst[m][k] = *(const PG8_LAS bf16x8*)(lds + PG8_SA(b, h) + aoff + m * 2048 + k * 1024); } while (0)
; #define PG8_LDB(dst, b, h) do { _Pragma("unroll") for (int n = 0; n < 2; ++n) _Pragma("unroll") for (int k = 0; k < 2; ++k) dst[n][k] = *(const PG8_LAS bf16x8*)(lds + PG8_SB(b, h) + boff + n * 2048 + k * 1024); } while (0)
; #define PG8_MMA(ai, bj, At, Bt) do { __builtin_amdgcn_s_setprio(1); _Pragma("unroll") for (int m = 0; m < 4; ++m) _Pragma("unroll") for (int n = 0; n < 2; ++n) _Pragma("unroll") for (int k = 0; k < 2; ++k) \
;         acc[ai][bj][m][n] = __builtin_amdgcn_mfma_f32_16x16x32_bf16(Bt[n][k], At[m][k], acc[ai][bj][m][n], 0, 0, 0); __builtin_amdgcn_s_setprio(0); } while (0)
; #define PG8_WAIT_V(n) asm volatile("s_waitcnt vmcnt(" #n ")" ::: "memory")
; #define PG8_BAR __builtin_amdgcn_s_barrier()
; template <class Epi, class Sched, bool ALIGN_EPI = false, bool SP2 = false>
; __device__ __forceinline__ void gemm_phase(PG8_LAS unsigned char* lds, const Gemm g, const Sched& S, const Epi& E, int tid_in) {
;     ...
;         for (int t = 0; t < nt; t += 2) {
;             const bool last = (t == nt - 2);
;             const char* a1 = cA + (size_t)(t + 1) * kstep;
;             const char* a2 = last ? nA : cA + (size_t)(t + 2) * kstep; const char* b2 = last ? nB : cB + (size_t)(t + 2) * kstep;
;             const char* a3 = a2 + kstep; const char* b3 = b2 + kstep;
;             if (last && has_next) S.a_ready(nxt);
;             if constexpr (SP2) {
;             PG8_LDB(B0, 0, 0); PG8_LDB(B1, 0, 1); PG8_SCHED; PG8_LDA(At, 0, 0); PG8_STAGE(PG8_SA(1, 1), a1 + hstepA, voffA);
;             PG8_WAIT_V(8); PG8_WAIT_L(0); PG8_BAR; PG8_MMA(0, 0, At, B0); PG8_MMA(0, 1, At, B1); PG8_BAR; PG8_SCHED;
;             PG8_LDA(At, 0, 1); PG8_STAGE(PG8_SB(0, 0), b2, voffB); PG8_STAGE(PG8_SB(0, 1), b2 + hstep, voffB); PG8_STAGE(PG8_SA(0, 0), a2, voffA);
;             PG8_WAIT_V(8); PG8_WAIT_L(0); PG8_BAR; PG8_MMA(1, 0, At, B0); PG8_MMA(1, 1, At, B1); PG8_BAR; PG8_SCHED;
.LBB0_276:
	s_add_i32 s56, s15, 2
	s_add_u32 s54, s38, 0xfff80080
	s_addc_u32 s55, s39, -1
	s_add_i32 s57, 0, 0x10000
	s_cmp_eq_u32 s68, s15
	s_cselect_b32 s55, s12, s55
	s_cselect_b32 s54, s13, s54
	v_add_u32_e32 v0, s57, v170
	s_cselect_b32 s75, s51, s49
	s_cselect_b32 s74, s50, s21
	s_add_i32 s15, 0, 0x14000
	ds_read_b128 v[130:133], v0
	ds_read_b128 v[152:155], v0 offset:1024
	ds_read_b128 v[178:181], v0 offset:2048
	ds_read_b128 v[182:185], v0 offset:3072
	v_add_u32_e32 v0, s15, v170
	ds_read_b128 v[186:189], v0
	ds_read_b128 v[190:193], v0 offset:1024
	ds_read_b128 v[204:207], v0 offset:2048
	ds_read_b128 v[208:211], v0 offset:3072
	v_lshl_add_u64 v[146:147], s[38:39], 0, v[148:149]
	s_add_i32 m0, s61, 0xc000
	ds_read_b128 v[212:215], v176
	ds_read_b128 v[216:219], v176 offset:1024
	ds_read_b128 v[220:223], v176 offset:2048
	ds_read_b128 v[224:227], v176 offset:3072
	ds_read_b128 v[228:231], v176 offset:4096
	ds_read_b128 v[232:235], v176 offset:5120
	ds_read_b128 v[236:239], v176 offset:6144
	ds_read_b128 v[240:243], v176 offset:7168
	global_load_lds_dwordx4 v[146:147], off
	v_lshl_add_u64 v[146:147], s[38:39], 0, v[150:151]
	s_add_i32 m0, s61, 0xe000
	s_nop 0
	global_load_lds_dwordx4 v[146:147], off
	s_waitcnt vmcnt(8)
	s_waitcnt lgkmcnt(0)
	s_barrier
	s_setprio 1
	s_waitcnt lgkmcnt(0)
	v_mfma_f32_16x16x32_bf16 v[126:129], v[130:133], v[212:215], v[126:129]
	v_mfma_f32_16x16x32_bf16 v[122:125], v[178:181], v[212:215], v[122:125]
	v_mfma_f32_16x16x32_bf16 v[110:113], v[130:133], v[220:223], v[110:113]
	v_mfma_f32_16x16x32_bf16 v[106:109], v[178:181], v[220:223], v[106:109]
	v_mfma_f32_16x16x32_bf16 v[94:97], v[130:133], v[228:231], v[94:97]
	v_mfma_f32_16x16x32_bf16 v[90:93], v[178:181], v[228:231], v[90:93]
	v_mfma_f32_16x16x32_bf16 v[78:81], v[130:133], v[236:239], v[78:81]
	v_mfma_f32_16x16x32_bf16 v[74:77], v[178:181], v[236:239], v[74:77]
	v_mfma_f32_16x16x32_bf16 v[126:129], v[152:155], v[216:219], v[126:129]
	v_mfma_f32_16x16x32_bf16 v[122:125], v[182:185], v[216:219], v[122:125]
	v_mfma_f32_16x16x32_bf16 v[110:113], v[152:155], v[224:227], v[110:113]
	v_mfma_f32_16x16x32_bf16 v[106:109], v[182:185], v[224:227], v[106:109]
	v_mfma_f32_16x16x32_bf16 v[94:97], v[152:155], v[232:235], v[94:97]
	v_mfma_f32_16x16x32_bf16 v[90:93], v[182:185], v[232:235], v[90:93]
	v_mfma_f32_16x16x32_bf16 v[78:81], v[152:155], v[240:243], v[78:81]
	v_mfma_f32_16x16x32_bf16 v[74:77], v[182:185], v[240:243], v[74:77]
	v_mfma_f32_16x16x32_bf16 v[118:121], v[186:189], v[212:215], v[118:121]
	v_mfma_f32_16x16x32_bf16 v[114:117], v[204:207], v[212:215], v[114:117]
	v_mfma_f32_16x16x32_bf16 v[102:105], v[186:189], v[220:223], v[102:105]
	v_mfma_f32_16x16x32_bf16 v[98:101], v[204:207], v[220:223], v[98:101]
	v_mfma_f32_16x16x32_bf16 v[86:89], v[186:189], v[228:231], v[86:89]
	v_mfma_f32_16x16x32_bf16 v[82:85], v[204:207], v[228:231], v[82:85]
	v_mfma_f32_16x16x32_bf16 v[70:73], v[186:189], v[236:239], v[70:73]
	v_mfma_f32_16x16x32_bf16 v[66:69], v[204:207], v[236:239], v[66:69]
	v_mfma_f32_16x16x32_bf16 v[118:121], v[190:193], v[216:219], v[118:121]
	v_mfma_f32_16x16x32_bf16 v[114:117], v[208:211], v[216:219], v[114:117]
	v_mfma_f32_16x16x32_bf16 v[102:105], v[190:193], v[224:227], v[102:105]
	v_mfma_f32_16x16x32_bf16 v[98:101], v[208:211], v[224:227], v[98:101]
	v_mfma_f32_16x16x32_bf16 v[86:89], v[190:193], v[232:235], v[86:89]
	v_mfma_f32_16x16x32_bf16 v[82:85], v[208:211], v[232:235], v[82:85]
	v_mfma_f32_16x16x32_bf16 v[70:73], v[190:193], v[240:243], v[70:73]
	v_mfma_f32_16x16x32_bf16 v[66:69], v[208:211], v[240:243], v[66:69]
	s_setprio 0
	s_barrier
	s_add_i32 s57, s57, s60
	v_lshl_add_u64 v[146:147], s[74:75], 0, v[138:139]
	s_mov_b32 m0, s57
	ds_read_b128 v[212:215], v176 offset:16384
	ds_read_b128 v[216:219], v176 offset:17408
	ds_read_b128 v[220:223], v176 offset:18432
	ds_read_b128 v[224:227], v176 offset:19456
	ds_read_b128 v[228:231], v176 offset:20480
	ds_read_b128 v[232:235], v176 offset:21504
	ds_read_b128 v[236:239], v176 offset:22528
	ds_read_b128 v[240:243], v176 offset:23552
	global_load_lds_dwordx4 v[146:147], off
	s_add_i32 m0, s57, 0x2000
	v_lshl_add_u64 v[194:195], s[74:75], 0, v[140:141]
	s_add_u32 s74, s74, s0
	s_addc_u32 s75, s75, s1
	s_add_i32 s15, s15, s60
	global_load_lds_dwordx4 v[194:195], off
	v_lshl_add_u64 v[244:245], s[74:75], 0, v[138:139]
	s_mov_b32 m0, s15
	v_lshl_add_u64 v[246:247], s[74:75], 0, v[140:141]
	global_load_lds_dwordx4 v[244:245], off
	s_add_i32 m0, s15, 0x2000
	v_lshl_add_u64 v[248:249], s[54:55], 0, v[134:135]
	global_load_lds_dwordx4 v[246:247], off
	s_mov_b32 m0, s61
	v_lshl_add_u64 v[250:251], s[54:55], 0, v[136:137]
	global_load_lds_dwordx4 v[248:249], off
	s_mov_b32 m0, s62
	s_nop 0
	global_load_lds_dwordx4 v[250:251], off
	s_waitcnt vmcnt(8)
	s_waitcnt lgkmcnt(0)
	s_barrier
; #define PG8_STAGE(bufoff, gbase, voff) do { _Pragma("unroll") for (int _i = 0; _i < 2; ++_i) \
;         __builtin_amdgcn_global_load_lds((const unsigned*)((const char*)(gbase) + (voff)[_i]), (PG8_LAS unsigned*)(lds + (bufoff) + ldsw + _i * 8192), 16, 0, 0); } while (0)
; #define PG8_LDA(dst, b, h) do { _Pragma("unroll") for (int m = 0; m < 4; ++m) _Pragma("unroll") for (int k = 0; k < 2; ++k) dst[m][k] = *(const PG8_LAS bf16x8*)(lds + PG8_SA(b, h) + aoff + m * 2048 + k * 1024); } while (0)
; #define PG8_LDB(dst, b, h) do { _Pragma("unroll") for (int n = 0; n < 2; ++n) _Pragma("unroll") for (int k = 0; k < 2; ++k) dst[n][k] = *(const PG8_LAS bf16x8*)(lds + PG8_SB(b, h) + boff + n * 2048 + k * 1024); } while (0)
; #define PG8_MMA(ai, bj, At, Bt) do { __builtin_amdgcn_s_setprio(1); _Pragma("unroll") for (int m = 0; m < 4; ++m) _Pragma("unroll") for (int n = 0; n < 2; ++n) _Pragma("unroll") for (int k = 0; k < 2; ++k) \
;         acc[ai][bj][m][n] = __builtin_amdgcn_mfma_f32_16x16x32_bf16(Bt[n][k], At[m][k], acc[ai][bj][m][n], 0, 0, 0); __builtin_amdgcn_s_setprio(0); } while (0)
; #define PG8_WAIT_V(n) asm volatile("s_waitcnt vmcnt(" #n ")" ::: "memory")
; #define PG8_WAIT_L(n) asm volatile("s_waitcnt lgkmcnt(" #n ")" ::: "memory")
; #define PG8_BAR __builtin_amdgcn_s_barrier()
; #define PG8_SCHED __builtin_amdgcn_sched_barrier(0)
; template <class Epi, class Sched, bool ALIGN_EPI = false, bool SP2 = false>
; __device__ __forceinline__ void gemm_phase(PG8_LAS unsigned char* lds, const Gemm g, const Sched& S, const Epi& E, int tid_in) {
;     ...
;             PG8_WAIT_V(8); PG8_WAIT_L(0); PG8_BAR; PG8_MMA(1, 0, At, B0); PG8_MMA(1, 1, At, B1); PG8_BAR; PG8_SCHED;
;             PG8_LDB(B0, 1, 0); PG8_LDB(B1, 1, 1); PG8_SCHED; PG8_LDA(At, 1, 0); PG8_STAGE(PG8_SA(0, 1), a2 + hstepA, voffA);
;             PG8_WAIT_V(8); PG8_WAIT_L(0); PG8_BAR; PG8_MMA(0, 0, At, B0); PG8_MMA(0, 1, At, B1); PG8_BAR; PG8_SCHED;
	s_setprio 1
	s_waitcnt lgkmcnt(0)
	v_mfma_f32_16x16x32_bf16 v[62:65], v[130:133], v[212:215], v[62:65]
	v_mfma_f32_16x16x32_bf16 v[58:61], v[178:181], v[212:215], v[58:61]
	v_mfma_f32_16x16x32_bf16 v[46:49], v[130:133], v[220:223], v[46:49]
	v_mfma_f32_16x16x32_bf16 v[42:45], v[178:181], v[220:223], v[42:45]
	v_mfma_f32_16x16x32_bf16 v[30:33], v[130:133], v[228:231], v[30:33]
	v_mfma_f32_16x16x32_bf16 v[26:29], v[178:181], v[228:231], v[26:29]
	v_mfma_f32_16x16x32_bf16 v[14:17], v[130:133], v[236:239], v[14:17]
	v_mfma_f32_16x16x32_bf16 v[10:13], v[178:181], v[236:239], v[10:13]
	v_mfma_f32_16x16x32_bf16 v[62:65], v[152:155], v[216:219], v[62:65]
	v_mfma_f32_16x16x32_bf16 v[58:61], v[182:185], v[216:219], v[58:61]
	v_mfma_f32_16x16x32_bf16 v[46:49], v[152:155], v[224:227], v[46:49]
	v_mfma_f32_16x16x32_bf16 v[42:45], v[182:185], v[224:227], v[42:45]
	v_mfma_f32_16x16x32_bf16 v[30:33], v[152:155], v[232:235], v[30:33]
	v_mfma_f32_16x16x32_bf16 v[26:29], v[182:185], v[232:235], v[26:29]
	v_mfma_f32_16x16x32_bf16 v[14:17], v[152:155], v[240:243], v[14:17]
	v_mfma_f32_16x16x32_bf16 v[10:13], v[182:185], v[240:243], v[10:13]
	v_mfma_f32_16x16x32_bf16 v[54:57], v[186:189], v[212:215], v[54:57]
	v_mfma_f32_16x16x32_bf16 v[50:53], v[204:207], v[212:215], v[50:53]
	v_mfma_f32_16x16x32_bf16 v[38:41], v[186:189], v[220:223], v[38:41]
	v_mfma_f32_16x16x32_bf16 v[34:37], v[204:207], v[220:223], v[34:37]
	v_mfma_f32_16x16x32_bf16 v[22:25], v[186:189], v[228:231], v[22:25]
	v_mfma_f32_16x16x32_bf16 v[18:21], v[204:207], v[228:231], v[18:21]
	v_mfma_f32_16x16x32_bf16 v[6:9], v[186:189], v[236:239], v[6:9]
	v_mfma_f32_16x16x32_bf16 v[2:5], v[204:207], v[236:239], v[2:5]
	v_mfma_f32_16x16x32_bf16 v[54:57], v[190:193], v[216:219], v[54:57]
	v_mfma_f32_16x16x32_bf16 v[50:53], v[208:211], v[216:219], v[50:53]
	v_mfma_f32_16x16x32_bf16 v[38:41], v[190:193], v[224:227], v[38:41]
	v_mfma_f32_16x16x32_bf16 v[34:37], v[208:211], v[224:227], v[34:37]
	v_mfma_f32_16x16x32_bf16 v[22:25], v[190:193], v[232:235], v[22:25]
	v_mfma_f32_16x16x32_bf16 v[18:21], v[208:211], v[232:235], v[18:21]
	v_mfma_f32_16x16x32_bf16 v[6:9], v[190:193], v[240:243], v[6:9]
	v_mfma_f32_16x16x32_bf16 v[2:5], v[208:211], v[240:243], v[2:5]
	s_setprio 0
	s_barrier
	s_add_i32 s15, 0, 0x18000
	v_add_u32_e32 v0, s15, v170
	s_add_i32 s57, 0, 0x1c000
	ds_read_b128 v[130:133], v0
	ds_read_b128 v[152:155], v0 offset:1024
	ds_read_b128 v[178:181], v0 offset:2048
	ds_read_b128 v[182:185], v0 offset:3072
	v_add_u32_e32 v0, s57, v170
	ds_read_b128 v[186:189], v0
	ds_read_b128 v[190:193], v0 offset:1024
	ds_read_b128 v[204:207], v0 offset:2048
	ds_read_b128 v[208:211], v0 offset:3072
	s_add_u32 s54, s54, 0x80000
	s_addc_u32 s55, s55, 0
	s_mov_b32 m0, s63
	v_lshl_add_u64 v[200:201], s[54:55], 0, v[134:135]
	ds_read_b128 v[212:215], v176 offset:32768
	ds_read_b128 v[216:219], v176 offset:33792
	ds_read_b128 v[220:223], v176 offset:34816
	ds_read_b128 v[224:227], v176 offset:35840
	ds_read_b128 v[228:231], v176 offset:36864
	ds_read_b128 v[232:235], v176 offset:37888
	ds_read_b128 v[236:239], v176 offset:38912
	ds_read_b128 v[240:243], v176 offset:39936
	global_load_lds_dwordx4 v[200:201], off
	v_lshl_add_u64 v[200:201], s[54:55], 0, v[136:137]
	s_mov_b32 m0, s64
	s_nop 0
	global_load_lds_dwordx4 v[200:201], off
	s_waitcnt vmcnt(8)
	s_waitcnt lgkmcnt(0)
	s_barrier
	s_setprio 1
	s_waitcnt lgkmcnt(0)
	v_mfma_f32_16x16x32_bf16 v[126:129], v[130:133], v[212:215], v[126:129]
	v_mfma_f32_16x16x32_bf16 v[122:125], v[178:181], v[212:215], v[122:125]
	v_mfma_f32_16x16x32_bf16 v[110:113], v[130:133], v[220:223], v[110:113]
	v_mfma_f32_16x16x32_bf16 v[106:109], v[178:181], v[220:223], v[106:109]
	v_mfma_f32_16x16x32_bf16 v[94:97], v[130:133], v[228:231], v[94:97]
	v_mfma_f32_16x16x32_bf16 v[90:93], v[178:181], v[228:231], v[90:93]
	v_mfma_f32_16x16x32_bf16 v[78:81], v[130:133], v[236:239], v[78:81]
	v_mfma_f32_16x16x32_bf16 v[74:77], v[178:181], v[236:239], v[74:77]
	v_mfma_f32_16x16x32_bf16 v[126:129], v[152:155], v[216:219], v[126:129]
	v_mfma_f32_16x16x32_bf16 v[122:125], v[182:185], v[216:219], v[122:125]
	v_mfma_f32_16x16x32_bf16 v[110:113], v[152:155], v[224:227], v[110:113]
	v_mfma_f32_16x16x32_bf16 v[106:109], v[182:185], v[224:227], v[106:109]
	v_mfma_f32_16x16x32_bf16 v[94:97], v[152:155], v[232:235], v[94:97]
	v_mfma_f32_16x16x32_bf16 v[90:93], v[182:185], v[232:235], v[90:93]
	v_mfma_f32_16x16x32_bf16 v[78:81], v[152:155], v[240:243], v[78:81]
	v_mfma_f32_16x16x32_bf16 v[74:77], v[182:185], v[240:243], v[74:77]
	v_mfma_f32_16x16x32_bf16 v[118:121], v[186:189], v[212:215], v[118:121]
	v_mfma_f32_16x16x32_bf16 v[114:117], v[204:207], v[212:215], v[114:117]
	v_mfma_f32_16x16x32_bf16 v[102:105], v[186:189], v[220:223], v[102:105]
	v_mfma_f32_16x16x32_bf16 v[98:101], v[204:207], v[220:223], v[98:101]
	v_mfma_f32_16x16x32_bf16 v[86:89], v[186:189], v[228:231], v[86:89]
	v_mfma_f32_16x16x32_bf16 v[82:85], v[204:207], v[228:231], v[82:85]
	v_mfma_f32_16x16x32_bf16 v[70:73], v[186:189], v[236:239], v[70:73]
	v_mfma_f32_16x16x32_bf16 v[66:69], v[204:207], v[236:239], v[66:69]
	v_mfma_f32_16x16x32_bf16 v[118:121], v[190:193], v[216:219], v[118:121]
	v_mfma_f32_16x16x32_bf16 v[114:117], v[208:211], v[216:219], v[114:117]
	v_mfma_f32_16x16x32_bf16 v[102:105], v[190:193], v[224:227], v[102:105]
	v_mfma_f32_16x16x32_bf16 v[98:101], v[208:211], v[224:227], v[98:101]
	v_mfma_f32_16x16x32_bf16 v[86:89], v[190:193], v[232:235], v[86:89]
	v_mfma_f32_16x16x32_bf16 v[82:85], v[208:211], v[232:235], v[82:85]
	v_mfma_f32_16x16x32_bf16 v[70:73], v[190:193], v[240:243], v[70:73]
	v_mfma_f32_16x16x32_bf16 v[66:69], v[208:211], v[240:243], v[66:69]
	s_setprio 0
	s_barrier
; #define PG8_STAGE(bufoff, gbase, voff) do { _Pragma("unroll") for (int _i = 0; _i < 2; ++_i) \
;         __builtin_amdgcn_global_load_lds((const unsigned*)((const char*)(gbase) + (voff)[_i]), (PG8_LAS unsigned*)(lds + (bufoff) + ldsw + _i * 8192), 16, 0, 0); } while (0)
; #define PG8_LDA(dst, b, h) do { _Pragma("unroll") for (int m = 0; m < 4; ++m) _Pragma("unroll") for (int k = 0; k < 2; ++k) dst[m][k] = *(const PG8_LAS bf16x8*)(lds + PG8_SA(b, h) + aoff + m * 2048 + k * 1024); } while (0)
; #define PG8_MMA(ai, bj, At, Bt) do { __builtin_amdgcn_s_setprio(1); _Pragma("unroll") for (int m = 0; m < 4; ++m) _Pragma("unroll") for (int n = 0; n < 2; ++n) _Pragma("unroll") for (int k = 0; k < 2; ++k) \
;         acc[ai][bj][m][n] = __builtin_amdgcn_mfma_f32_16x16x32_bf16(Bt[n][k], At[m][k], acc[ai][bj][m][n], 0, 0, 0); __builtin_amdgcn_s_setprio(0); } while (0)
; #define PG8_WAIT_V(n) asm volatile("s_waitcnt vmcnt(" #n ")" ::: "memory")
; #define PG8_WAIT_L(n) asm volatile("s_waitcnt lgkmcnt(" #n ")" ::: "memory")
; #define PG8_BAR __builtin_amdgcn_s_barrier()
; #define PG8_SCHED __builtin_amdgcn_sched_barrier(0)
; template <class Epi, class Sched, bool ALIGN_EPI = false, bool SP2 = false>
; __device__ __forceinline__ void gemm_phase(PG8_LAS unsigned char* lds, const Gemm g, const Sched& S, const Epi& E, int tid_in) {
;     ...
;             PG8_LDA(At, 1, 1); PG8_STAGE(PG8_SB(1, 0), b3, voffB); PG8_STAGE(PG8_SB(1, 1), b3 + hstep, voffB); PG8_STAGE(PG8_SA(1, 0), a3, voffA);
;             PG8_WAIT_V(8); PG8_WAIT_L(0); PG8_BAR; PG8_MMA(1, 0, At, B0); PG8_MMA(1, 1, At, B1); PG8_BAR; PG8_SCHED;
	s_add_i32 s15, s15, s60
	v_lshl_add_u64 v[146:147], v[146:147], 0, s[28:29]
	s_mov_b32 m0, s15
	ds_read_b128 v[212:215], v176 offset:49152
	ds_read_b128 v[216:219], v176 offset:50176
	ds_read_b128 v[220:223], v176 offset:51200
	ds_read_b128 v[224:227], v176 offset:52224
	ds_read_b128 v[228:231], v176 offset:53248
	ds_read_b128 v[232:235], v176 offset:54272
	ds_read_b128 v[236:239], v176 offset:55296
	ds_read_b128 v[240:243], v176 offset:56320
	global_load_lds_dwordx4 v[146:147], off
	v_lshl_add_u64 v[146:147], v[194:195], 0, s[28:29]
	s_add_i32 m0, s15, 0x2000
	s_add_i32 s15, s57, s60
	global_load_lds_dwordx4 v[146:147], off
	v_lshl_add_u64 v[146:147], v[244:245], 0, s[28:29]
	s_mov_b32 m0, s15
	s_nop 0
	global_load_lds_dwordx4 v[146:147], off
	v_lshl_add_u64 v[146:147], v[246:247], 0, s[28:29]
	s_add_i32 m0, s15, 0x2000
	s_nop 0
	global_load_lds_dwordx4 v[146:147], off
	v_lshl_add_u64 v[146:147], v[248:249], 0, s[28:29]
	s_mov_b32 m0, s65
	s_nop 0
	global_load_lds_dwordx4 v[146:147], off
	v_lshl_add_u64 v[146:147], v[250:251], 0, s[28:29]
	s_mov_b32 m0, s66
	s_nop 0
	global_load_lds_dwordx4 v[146:147], off
	s_waitcnt vmcnt(8)
	s_waitcnt lgkmcnt(0)
	s_barrier
	s_setprio 1
	s_waitcnt lgkmcnt(0)
	v_mfma_f32_16x16x32_bf16 v[62:65], v[130:133], v[212:215], v[62:65]
	v_mfma_f32_16x16x32_bf16 v[58:61], v[178:181], v[212:215], v[58:61]
	v_mfma_f32_16x16x32_bf16 v[46:49], v[130:133], v[220:223], v[46:49]
	v_mfma_f32_16x16x32_bf16 v[42:45], v[178:181], v[220:223], v[42:45]
	v_mfma_f32_16x16x32_bf16 v[30:33], v[130:133], v[228:231], v[30:33]
	v_mfma_f32_16x16x32_bf16 v[26:29], v[178:181], v[228:231], v[26:29]
	v_mfma_f32_16x16x32_bf16 v[14:17], v[130:133], v[236:239], v[14:17]
	v_mfma_f32_16x16x32_bf16 v[10:13], v[178:181], v[236:239], v[10:13]
	v_mfma_f32_16x16x32_bf16 v[62:65], v[152:155], v[216:219], v[62:65]
	v_mfma_f32_16x16x32_bf16 v[58:61], v[182:185], v[216:219], v[58:61]
	v_mfma_f32_16x16x32_bf16 v[46:49], v[152:155], v[224:227], v[46:49]
	v_mfma_f32_16x16x32_bf16 v[42:45], v[182:185], v[224:227], v[42:45]
	v_mfma_f32_16x16x32_bf16 v[30:33], v[152:155], v[232:235], v[30:33]
	v_mfma_f32_16x16x32_bf16 v[26:29], v[182:185], v[232:235], v[26:29]
	v_mfma_f32_16x16x32_bf16 v[14:17], v[152:155], v[240:243], v[14:17]
	v_mfma_f32_16x16x32_bf16 v[10:13], v[182:185], v[240:243], v[10:13]
	v_mfma_f32_16x16x32_bf16 v[54:57], v[186:189], v[212:215], v[54:57]
	v_mfma_f32_16x16x32_bf16 v[50:53], v[204:207], v[212:215], v[50:53]
	v_mfma_f32_16x16x32_bf16 v[38:41], v[186:189], v[220:223], v[38:41]
	v_mfma_f32_16x16x32_bf16 v[34:37], v[204:207], v[220:223], v[34:37]
	v_mfma_f32_16x16x32_bf16 v[22:25], v[186:189], v[228:231], v[22:25]
	v_mfma_f32_16x16x32_bf16 v[18:21], v[204:207], v[228:231], v[18:21]
	v_mfma_f32_16x16x32_bf16 v[6:9], v[186:189], v[236:239], v[6:9]
	v_mfma_f32_16x16x32_bf16 v[2:5], v[204:207], v[236:239], v[2:5]
	v_mfma_f32_16x16x32_bf16 v[54:57], v[190:193], v[216:219], v[54:57]
	v_mfma_f32_16x16x32_bf16 v[50:53], v[208:211], v[216:219], v[50:53]
	v_mfma_f32_16x16x32_bf16 v[38:41], v[190:193], v[224:227], v[38:41]
	v_mfma_f32_16x16x32_bf16 v[34:37], v[208:211], v[224:227], v[34:37]
	v_mfma_f32_16x16x32_bf16 v[22:25], v[190:193], v[232:235], v[22:25]
	v_mfma_f32_16x16x32_bf16 v[18:21], v[208:211], v[232:235], v[18:21]
	v_mfma_f32_16x16x32_bf16 v[6:9], v[190:193], v[240:243], v[6:9]
	v_mfma_f32_16x16x32_bf16 v[2:5], v[208:211], v[240:243], v[2:5]
	s_setprio 0
	s_barrier
	s_add_u32 s38, s38, 0x100
	s_addc_u32 s39, s39, 0
	s_add_u32 s21, s21, 0x100
	s_addc_u32 s49, s49, 0
	s_cmp_ge_i32 s56, s67
	s_mov_b32 s15, s56
	s_cbranch_scc0 .LBB0_276

; #define PG8_STAGE(bufoff, gbase, voff) do { _Pragma("unroll") for (int _i = 0; _i < 2; ++_i) \
;         __builtin_amdgcn_global_load_lds((const unsigned*)((const char*)(gbase) + (voff)[_i]), (PG8_LAS unsigned*)(lds + (bufoff) + ldsw + _i * 8192), 16, 0, 0); } while (0)
; #define PG8_LDA(dst, b, h) do { _Pragma("unroll") for (int m = 0; m < 4; ++m) _Pragma("unroll") for (int k = 0; k < 2; ++k) dst[m][k] = *(const PG8_LAS bf16x8*)(lds + PG8_SA(b, h) + aoff + m * 2048 + k * 1024); } while (0)
; #define PG8_LDB(dst, b, h) do { _Pragma("unroll") for (int n = 0; n < 2; ++n) _Pragma("unroll") for (int k = 0; k < 2; ++k) dst[n][k] = *(const PG8_LAS bf16x8*)(lds + PG8_SB(b, h) + boff + n * 2048 + k * 1024); } while (0)
; #define PG8_MMA(ai, bj, At, Bt) do { __builtin_amdgcn_s_setprio(1); _Pragma("unroll") for (int m = 0; m < 4; ++m) _Pragma("unroll") for (int n = 0; n < 2; ++n) _Pragma("unroll") for (int k = 0; k < 2; ++k) \
;         acc[ai][bj][m][n] = __builtin_amdgcn_mfma_f32_16x16x32_bf16(Bt[n][k], At[m][k], acc[ai][bj][m][n], 0, 0, 0); __builtin_amdgcn_s_setprio(0); } while (0)
; #define PG8_WAIT_V(n) asm volatile("s_waitcnt vmcnt(" #n ")" ::: "memory")
; #define PG8_BAR __builtin_amdgcn_s_barrier()
; template <class Epi, class Sched, bool ALIGN_EPI = false, bool SP2 = false>
; __device__ __forceinline__ void gemm_phase(PG8_LAS unsigned char* lds, const Gemm g, const Sched& S, const Epi& E, int tid_in) {
;     ...
;         for (int t = 0; t < nt; t += 2) {
;             const bool last = (t == nt - 2);
;             const char* a1 = cA + (size_t)(t + 1) * kstep;
;             const char* a2 = last ? nA : cA + (size_t)(t + 2) * kstep; const char* b2 = last ? nB : cB + (size_t)(t + 2) * kstep;
;             const char* a3 = a2 + kstep; const char* b3 = b2 + kstep;
;             if (last && has_next) S.a_ready(nxt);
;             if constexpr (SP2) {
;             PG8_LDB(B0, 0, 0); PG8_LDB(B1, 0, 1); PG8_SCHED; PG8_LDA(At, 0, 0); PG8_STAGE(PG8_SA(1, 1), a1 + hstepA, voffA);
;             PG8_WAIT_V(8); PG8_WAIT_L(0); PG8_BAR; PG8_MMA(0, 0, At, B0); PG8_MMA(0, 1, At, B1); PG8_BAR; PG8_SCHED;
;             PG8_LDA(At, 0, 1); PG8_STAGE(PG8_SB(0, 0), b2, voffB); PG8_STAGE(PG8_SB(0, 1), b2 + hstep, voffB); PG8_STAGE(PG8_SA(0, 0), a2, voffA);
;             PG8_WAIT_V(8); PG8_WAIT_L(0); PG8_BAR; PG8_MMA(1, 0, At, B0); PG8_MMA(1, 1, At, B1); PG8_BAR; PG8_SCHED;
.LBB0_353:
	s_add_i32 s24, s15, 2
	s_add_u32 s47, s52, 0xfff80080
	s_addc_u32 s54, s53, -1
	s_add_i32 s76, 0, 0x10000
	s_cmp_eq_u32 s69, s15
	s_cselect_b32 s55, s49, s54
	s_cselect_b32 s54, s48, s47
	v_add_u32_e32 v145, s76, v144
	s_cselect_b32 s75, s51, s13
	s_cselect_b32 s74, s50, s12
	s_add_i32 s15, 0, 0x14000
	ds_read_b128 v[146:149], v145
	ds_read_b128 v[150:153], v145 offset:1024
	ds_read_b128 v[154:157], v145 offset:2048
	ds_read_b128 v[158:161], v145 offset:3072
	v_add_u32_e32 v145, s15, v144
	ds_read_b128 v[162:165], v145
	ds_read_b128 v[166:169], v145 offset:1024
	ds_read_b128 v[170:173], v145 offset:2048
	ds_read_b128 v[174:177], v145 offset:3072
	v_lshl_add_u64 v[194:195], s[52:53], 0, v[138:139]
	s_add_i32 m0, s23, 0xc000
	ds_read_b128 v[178:181], v143
	ds_read_b128 v[182:185], v143 offset:1024
	ds_read_b128 v[186:189], v143 offset:2048
	ds_read_b128 v[190:193], v143 offset:3072
	ds_read_b128 v[204:207], v143 offset:4096
	ds_read_b128 v[208:211], v143 offset:5120
	ds_read_b128 v[212:215], v143 offset:6144
	ds_read_b128 v[216:219], v143 offset:7168
	global_load_lds_dwordx4 v[194:195], off
	v_lshl_add_u64 v[194:195], s[52:53], 0, v[140:141]
	s_add_i32 m0, s23, 0xe000
	s_nop 0
	global_load_lds_dwordx4 v[194:195], off
	s_waitcnt vmcnt(8)
	s_waitcnt lgkmcnt(0)
	s_barrier
	s_setprio 1
	s_waitcnt lgkmcnt(0)
	v_mfma_f32_16x16x32_bf16 v[122:125], v[146:149], v[178:181], v[122:125]
	v_mfma_f32_16x16x32_bf16 v[126:129], v[154:157], v[178:181], v[126:129]
	v_mfma_f32_16x16x32_bf16 v[110:113], v[146:149], v[186:189], v[110:113]
	v_mfma_f32_16x16x32_bf16 v[106:109], v[154:157], v[186:189], v[106:109]
	v_mfma_f32_16x16x32_bf16 v[94:97], v[146:149], v[204:207], v[94:97]
	v_mfma_f32_16x16x32_bf16 v[90:93], v[154:157], v[204:207], v[90:93]
	v_mfma_f32_16x16x32_bf16 v[78:81], v[146:149], v[212:215], v[78:81]
	v_mfma_f32_16x16x32_bf16 v[74:77], v[154:157], v[212:215], v[74:77]
	v_mfma_f32_16x16x32_bf16 v[122:125], v[150:153], v[182:185], v[122:125]
	v_mfma_f32_16x16x32_bf16 v[126:129], v[158:161], v[182:185], v[126:129]
	v_mfma_f32_16x16x32_bf16 v[110:113], v[150:153], v[190:193], v[110:113]
	v_mfma_f32_16x16x32_bf16 v[106:109], v[158:161], v[190:193], v[106:109]
	v_mfma_f32_16x16x32_bf16 v[94:97], v[150:153], v[208:211], v[94:97]
	v_mfma_f32_16x16x32_bf16 v[90:93], v[158:161], v[208:211], v[90:93]
	v_mfma_f32_16x16x32_bf16 v[78:81], v[150:153], v[216:219], v[78:81]
	v_mfma_f32_16x16x32_bf16 v[74:77], v[158:161], v[216:219], v[74:77]
	v_mfma_f32_16x16x32_bf16 v[118:121], v[162:165], v[178:181], v[118:121]
	v_mfma_f32_16x16x32_bf16 v[114:117], v[170:173], v[178:181], v[114:117]
	v_mfma_f32_16x16x32_bf16 v[102:105], v[162:165], v[186:189], v[102:105]
	v_mfma_f32_16x16x32_bf16 v[98:101], v[170:173], v[186:189], v[98:101]
	v_mfma_f32_16x16x32_bf16 v[86:89], v[162:165], v[204:207], v[86:89]
	v_mfma_f32_16x16x32_bf16 v[82:85], v[170:173], v[204:207], v[82:85]
	v_mfma_f32_16x16x32_bf16 v[70:73], v[162:165], v[212:215], v[70:73]
	v_mfma_f32_16x16x32_bf16 v[66:69], v[170:173], v[212:215], v[66:69]
	v_mfma_f32_16x16x32_bf16 v[118:121], v[166:169], v[182:185], v[118:121]
	v_mfma_f32_16x16x32_bf16 v[114:117], v[174:177], v[182:185], v[114:117]
	v_mfma_f32_16x16x32_bf16 v[102:105], v[166:169], v[190:193], v[102:105]
	v_mfma_f32_16x16x32_bf16 v[98:101], v[174:177], v[190:193], v[98:101]
	v_mfma_f32_16x16x32_bf16 v[86:89], v[166:169], v[208:211], v[86:89]
	v_mfma_f32_16x16x32_bf16 v[82:85], v[174:177], v[208:211], v[82:85]
	v_mfma_f32_16x16x32_bf16 v[70:73], v[166:169], v[216:219], v[70:73]
	v_mfma_f32_16x16x32_bf16 v[66:69], v[174:177], v[216:219], v[66:69]
	s_setprio 0
	s_barrier
	s_add_i32 s47, s76, s57
	v_lshl_add_u64 v[194:195], s[74:75], 0, v[130:131]
	s_mov_b32 m0, s47
	ds_read_b128 v[178:181], v143 offset:16384
	ds_read_b128 v[182:185], v143 offset:17408
	ds_read_b128 v[186:189], v143 offset:18432
	ds_read_b128 v[190:193], v143 offset:19456
	ds_read_b128 v[204:207], v143 offset:20480
	ds_read_b128 v[208:211], v143 offset:21504
	ds_read_b128 v[212:215], v143 offset:22528
	ds_read_b128 v[216:219], v143 offset:23552
	global_load_lds_dwordx4 v[194:195], off
	s_add_i32 m0, s47, 0x2000
	v_lshl_add_u64 v[200:201], s[74:75], 0, v[132:133]
	s_add_u32 s74, s74, s0
	s_addc_u32 s75, s75, s1
	s_add_i32 s15, s15, s57
	global_load_lds_dwordx4 v[200:201], off
	v_lshl_add_u64 v[220:221], s[74:75], 0, v[130:131]
	s_mov_b32 m0, s15
	v_lshl_add_u64 v[222:223], s[74:75], 0, v[132:133]
	global_load_lds_dwordx4 v[220:221], off
	s_add_i32 m0, s15, 0x2000
	v_lshl_add_u64 v[224:225], s[54:55], 0, v[134:135]
	global_load_lds_dwordx4 v[222:223], off
	s_mov_b32 m0, s23
	v_lshl_add_u64 v[226:227], s[54:55], 0, v[136:137]
	global_load_lds_dwordx4 v[224:225], off
	s_mov_b32 m0, s60
	s_nop 0
	global_load_lds_dwordx4 v[226:227], off
	s_waitcnt vmcnt(8)
	s_waitcnt lgkmcnt(0)
	s_barrier
; #define PG8_STAGE(bufoff, gbase, voff) do { _Pragma("unroll") for (int _i = 0; _i < 2; ++_i) \
;         __builtin_amdgcn_global_load_lds((const unsigned*)((const char*)(gbase) + (voff)[_i]), (PG8_LAS unsigned*)(lds + (bufoff) + ldsw + _i * 8192), 16, 0, 0); } while (0)
; #define PG8_LDA(dst, b, h) do { _Pragma("unroll") for (int m = 0; m < 4; ++m) _Pragma("unroll") for (int k = 0; k < 2; ++k) dst[m][k] = *(const PG8_LAS bf16x8*)(lds + PG8_SA(b, h) + aoff + m * 2048 + k * 1024); } while (0)
; #define PG8_LDB(dst, b, h) do { _Pragma("unroll") for (int n = 0; n < 2; ++n) _Pragma("unroll") for (int k = 0; k < 2; ++k) dst[n][k] = *(const PG8_LAS bf16x8*)(lds + PG8_SB(b, h) + boff + n * 2048 + k * 1024); } while (0)
; #define PG8_MMA(ai, bj, At, Bt) do { __builtin_amdgcn_s_setprio(1); _Pragma("unroll") for (int m = 0; m < 4; ++m) _Pragma("unroll") for (int n = 0; n < 2; ++n) _Pragma("unroll") for (int k = 0; k < 2; ++k) \
;         acc[ai][bj][m][n] = __builtin_amdgcn_mfma_f32_16x16x32_bf16(Bt[n][k], At[m][k], acc[ai][bj][m][n], 0, 0, 0); __builtin_amdgcn_s_setprio(0); } while (0)
; #define PG8_WAIT_V(n) asm volatile("s_waitcnt vmcnt(" #n ")" ::: "memory")
; #define PG8_WAIT_L(n) asm volatile("s_waitcnt lgkmcnt(" #n ")" ::: "memory")
; #define PG8_BAR __builtin_amdgcn_s_barrier()
; #define PG8_SCHED __builtin_amdgcn_sched_barrier(0)
; template <class Epi, class Sched, bool ALIGN_EPI = false, bool SP2 = false>
; __device__ __forceinline__ void gemm_phase(PG8_LAS unsigned char* lds, const Gemm g, const Sched& S, const Epi& E, int tid_in) {
;     ...
;             PG8_WAIT_V(8); PG8_WAIT_L(0); PG8_BAR; PG8_MMA(1, 0, At, B0); PG8_MMA(1, 1, At, B1); PG8_BAR; PG8_SCHED;
;             PG8_LDB(B0, 1, 0); PG8_LDB(B1, 1, 1); PG8_SCHED; PG8_LDA(At, 1, 0); PG8_STAGE(PG8_SA(0, 1), a2 + hstepA, voffA);
;             PG8_WAIT_V(8); PG8_WAIT_L(0); PG8_BAR; PG8_MMA(0, 0, At, B0); PG8_MMA(0, 1, At, B1); PG8_BAR; PG8_SCHED;
	s_setprio 1
	s_waitcnt lgkmcnt(0)
	v_mfma_f32_16x16x32_bf16 v[62:65], v[146:149], v[178:181], v[62:65]
	v_mfma_f32_16x16x32_bf16 v[58:61], v[154:157], v[178:181], v[58:61]
	v_mfma_f32_16x16x32_bf16 v[46:49], v[146:149], v[186:189], v[46:49]
	v_mfma_f32_16x16x32_bf16 v[42:45], v[154:157], v[186:189], v[42:45]
	v_mfma_f32_16x16x32_bf16 v[30:33], v[146:149], v[204:207], v[30:33]
	v_mfma_f32_16x16x32_bf16 v[26:29], v[154:157], v[204:207], v[26:29]
	v_mfma_f32_16x16x32_bf16 v[14:17], v[146:149], v[212:215], v[14:17]
	v_mfma_f32_16x16x32_bf16 v[10:13], v[154:157], v[212:215], v[10:13]
	v_mfma_f32_16x16x32_bf16 v[62:65], v[150:153], v[182:185], v[62:65]
	v_mfma_f32_16x16x32_bf16 v[58:61], v[158:161], v[182:185], v[58:61]
	v_mfma_f32_16x16x32_bf16 v[46:49], v[150:153], v[190:193], v[46:49]
	v_mfma_f32_16x16x32_bf16 v[42:45], v[158:161], v[190:193], v[42:45]
	v_mfma_f32_16x16x32_bf16 v[30:33], v[150:153], v[208:211], v[30:33]
	v_mfma_f32_16x16x32_bf16 v[26:29], v[158:161], v[208:211], v[26:29]
	v_mfma_f32_16x16x32_bf16 v[14:17], v[150:153], v[216:219], v[14:17]
	v_mfma_f32_16x16x32_bf16 v[10:13], v[158:161], v[216:219], v[10:13]
	v_mfma_f32_16x16x32_bf16 v[54:57], v[162:165], v[178:181], v[54:57]
	v_mfma_f32_16x16x32_bf16 v[50:53], v[170:173], v[178:181], v[50:53]
	v_mfma_f32_16x16x32_bf16 v[38:41], v[162:165], v[186:189], v[38:41]
	v_mfma_f32_16x16x32_bf16 v[34:37], v[170:173], v[186:189], v[34:37]
	v_mfma_f32_16x16x32_bf16 v[22:25], v[162:165], v[204:207], v[22:25]
	v_mfma_f32_16x16x32_bf16 v[18:21], v[170:173], v[204:207], v[18:21]
	v_mfma_f32_16x16x32_bf16 v[6:9], v[162:165], v[212:215], v[6:9]
	v_mfma_f32_16x16x32_bf16 v[2:5], v[170:173], v[212:215], v[2:5]
	v_mfma_f32_16x16x32_bf16 v[54:57], v[166:169], v[182:185], v[54:57]
	v_mfma_f32_16x16x32_bf16 v[50:53], v[174:177], v[182:185], v[50:53]
	v_mfma_f32_16x16x32_bf16 v[38:41], v[166:169], v[190:193], v[38:41]
	v_mfma_f32_16x16x32_bf16 v[34:37], v[174:177], v[190:193], v[34:37]
	v_mfma_f32_16x16x32_bf16 v[22:25], v[166:169], v[208:211], v[22:25]
	v_mfma_f32_16x16x32_bf16 v[18:21], v[174:177], v[208:211], v[18:21]
	v_mfma_f32_16x16x32_bf16 v[6:9], v[166:169], v[216:219], v[6:9]
	v_mfma_f32_16x16x32_bf16 v[2:5], v[174:177], v[216:219], v[2:5]
	s_setprio 0
	s_barrier
	s_add_i32 s15, 0, 0x18000
	v_add_u32_e32 v145, s15, v144
	s_add_i32 s47, 0, 0x1c000
	ds_read_b128 v[146:149], v145
	ds_read_b128 v[150:153], v145 offset:1024
	ds_read_b128 v[154:157], v145 offset:2048
	ds_read_b128 v[158:161], v145 offset:3072
	v_add_u32_e32 v145, s47, v144
	ds_read_b128 v[162:165], v145
	ds_read_b128 v[166:169], v145 offset:1024
	ds_read_b128 v[170:173], v145 offset:2048
	ds_read_b128 v[174:177], v145 offset:3072
	s_add_u32 s54, s54, 0x80000
	s_addc_u32 s55, s55, 0
	s_mov_b32 m0, s61
	v_lshl_add_u64 v[228:229], s[54:55], 0, v[134:135]
	ds_read_b128 v[178:181], v143 offset:32768
	ds_read_b128 v[182:185], v143 offset:33792
	ds_read_b128 v[186:189], v143 offset:34816
	ds_read_b128 v[190:193], v143 offset:35840
	ds_read_b128 v[204:207], v143 offset:36864
	ds_read_b128 v[208:211], v143 offset:37888
	ds_read_b128 v[212:215], v143 offset:38912
	ds_read_b128 v[216:219], v143 offset:39936
	global_load_lds_dwordx4 v[228:229], off
	v_lshl_add_u64 v[228:229], s[54:55], 0, v[136:137]
	s_mov_b32 m0, s62
	s_nop 0
	global_load_lds_dwordx4 v[228:229], off
	s_waitcnt vmcnt(8)
	s_waitcnt lgkmcnt(0)
	s_barrier
	s_setprio 1
	s_waitcnt lgkmcnt(0)
	v_mfma_f32_16x16x32_bf16 v[122:125], v[146:149], v[178:181], v[122:125]
	v_mfma_f32_16x16x32_bf16 v[126:129], v[154:157], v[178:181], v[126:129]
	v_mfma_f32_16x16x32_bf16 v[110:113], v[146:149], v[186:189], v[110:113]
	v_mfma_f32_16x16x32_bf16 v[106:109], v[154:157], v[186:189], v[106:109]
	v_mfma_f32_16x16x32_bf16 v[94:97], v[146:149], v[204:207], v[94:97]
	v_mfma_f32_16x16x32_bf16 v[90:93], v[154:157], v[204:207], v[90:93]
	v_mfma_f32_16x16x32_bf16 v[78:81], v[146:149], v[212:215], v[78:81]
	v_mfma_f32_16x16x32_bf16 v[74:77], v[154:157], v[212:215], v[74:77]
	v_mfma_f32_16x16x32_bf16 v[122:125], v[150:153], v[182:185], v[122:125]
	v_mfma_f32_16x16x32_bf16 v[126:129], v[158:161], v[182:185], v[126:129]
	v_mfma_f32_16x16x32_bf16 v[110:113], v[150:153], v[190:193], v[110:113]
	v_mfma_f32_16x16x32_bf16 v[106:109], v[158:161], v[190:193], v[106:109]
	v_mfma_f32_16x16x32_bf16 v[94:97], v[150:153], v[208:211], v[94:97]
	v_mfma_f32_16x16x32_bf16 v[90:93], v[158:161], v[208:211], v[90:93]
	v_mfma_f32_16x16x32_bf16 v[78:81], v[150:153], v[216:219], v[78:81]
	v_mfma_f32_16x16x32_bf16 v[74:77], v[158:161], v[216:219], v[74:77]
	v_mfma_f32_16x16x32_bf16 v[118:121], v[162:165], v[178:181], v[118:121]
	v_mfma_f32_16x16x32_bf16 v[114:117], v[170:173], v[178:181], v[114:117]
	v_mfma_f32_16x16x32_bf16 v[102:105], v[162:165], v[186:189], v[102:105]
	v_mfma_f32_16x16x32_bf16 v[98:101], v[170:173], v[186:189], v[98:101]
	v_mfma_f32_16x16x32_bf16 v[86:89], v[162:165], v[204:207], v[86:89]
	v_mfma_f32_16x16x32_bf16 v[82:85], v[170:173], v[204:207], v[82:85]
	v_mfma_f32_16x16x32_bf16 v[70:73], v[162:165], v[212:215], v[70:73]
	v_mfma_f32_16x16x32_bf16 v[66:69], v[170:173], v[212:215], v[66:69]
	v_mfma_f32_16x16x32_bf16 v[118:121], v[166:169], v[182:185], v[118:121]
	v_mfma_f32_16x16x32_bf16 v[114:117], v[174:177], v[182:185], v[114:117]
	v_mfma_f32_16x16x32_bf16 v[102:105], v[166:169], v[190:193], v[102:105]
	v_mfma_f32_16x16x32_bf16 v[98:101], v[174:177], v[190:193], v[98:101]
	v_mfma_f32_16x16x32_bf16 v[86:89], v[166:169], v[208:211], v[86:89]
	v_mfma_f32_16x16x32_bf16 v[82:85], v[174:177], v[208:211], v[82:85]
	v_mfma_f32_16x16x32_bf16 v[70:73], v[166:169], v[216:219], v[70:73]
	v_mfma_f32_16x16x32_bf16 v[66:69], v[174:177], v[216:219], v[66:69]
	s_setprio 0
	s_barrier
; #define PG8_STAGE(bufoff, gbase, voff) do { _Pragma("unroll") for (int _i = 0; _i < 2; ++_i) \
;         __builtin_amdgcn_global_load_lds((const unsigned*)((const char*)(gbase) + (voff)[_i]), (PG8_LAS unsigned*)(lds + (bufoff) + ldsw + _i * 8192), 16, 0, 0); } while (0)
; #define PG8_LDA(dst, b, h) do { _Pragma("unroll") for (int m = 0; m < 4; ++m) _Pragma("unroll") for (int k = 0; k < 2; ++k) dst[m][k] = *(const PG8_LAS bf16x8*)(lds + PG8_SA(b, h) + aoff + m * 2048 + k * 1024); } while (0)
; #define PG8_MMA(ai, bj, At, Bt) do { __builtin_amdgcn_s_setprio(1); _Pragma("unroll") for (int m = 0; m < 4; ++m) _Pragma("unroll") for (int n = 0; n < 2; ++n) _Pragma("unroll") for (int k = 0; k < 2; ++k) \
;         acc[ai][bj][m][n] = __builtin_amdgcn_mfma_f32_16x16x32_bf16(Bt[n][k], At[m][k], acc[ai][bj][m][n], 0, 0, 0); __builtin_amdgcn_s_setprio(0); } while (0)
; #define PG8_WAIT_V(n) asm volatile("s_waitcnt vmcnt(" #n ")" ::: "memory")
; #define PG8_WAIT_L(n) asm volatile("s_waitcnt lgkmcnt(" #n ")" ::: "memory")
; #define PG8_BAR __builtin_amdgcn_s_barrier()
; #define PG8_SCHED __builtin_amdgcn_sched_barrier(0)
; template <class Epi, class Sched, bool ALIGN_EPI = false, bool SP2 = false>
; __device__ __forceinline__ void gemm_phase(PG8_LAS unsigned char* lds, const Gemm g, const Sched& S, const Epi& E, int tid_in) {
;     ...
;             PG8_LDA(At, 1, 1); PG8_STAGE(PG8_SB(1, 0), b3, voffB); PG8_STAGE(PG8_SB(1, 1), b3 + hstep, voffB); PG8_STAGE(PG8_SA(1, 0), a3, voffA);
;             PG8_WAIT_V(8); PG8_WAIT_L(0); PG8_BAR; PG8_MMA(1, 0, At, B0); PG8_MMA(1, 1, At, B1); PG8_BAR; PG8_SCHED;
	s_add_i32 s15, s15, s57
	v_lshl_add_u64 v[194:195], v[194:195], 0, s[28:29]
	s_mov_b32 m0, s15
	ds_read_b128 v[178:181], v143 offset:49152
	ds_read_b128 v[182:185], v143 offset:50176
	ds_read_b128 v[186:189], v143 offset:51200
	ds_read_b128 v[190:193], v143 offset:52224
	ds_read_b128 v[204:207], v143 offset:53248
	ds_read_b128 v[208:211], v143 offset:54272
	ds_read_b128 v[212:215], v143 offset:55296
	ds_read_b128 v[216:219], v143 offset:56320
	global_load_lds_dwordx4 v[194:195], off
	v_lshl_add_u64 v[194:195], v[200:201], 0, s[28:29]
	s_add_i32 m0, s15, 0x2000
	s_add_i32 s15, s47, s57
	global_load_lds_dwordx4 v[194:195], off
	v_lshl_add_u64 v[194:195], v[220:221], 0, s[28:29]
	s_mov_b32 m0, s15
	s_nop 0
	global_load_lds_dwordx4 v[194:195], off
	v_lshl_add_u64 v[194:195], v[222:223], 0, s[28:29]
	s_add_i32 m0, s15, 0x2000
	s_nop 0
	global_load_lds_dwordx4 v[194:195], off
	v_lshl_add_u64 v[194:195], v[224:225], 0, s[28:29]
	s_mov_b32 m0, s65
	s_nop 0
	global_load_lds_dwordx4 v[194:195], off
	v_lshl_add_u64 v[194:195], v[226:227], 0, s[28:29]
	s_mov_b32 m0, s66
	s_nop 0
	global_load_lds_dwordx4 v[194:195], off
	s_waitcnt vmcnt(8)
	s_waitcnt lgkmcnt(0)
	s_barrier
	s_setprio 1
	s_waitcnt lgkmcnt(0)
	v_mfma_f32_16x16x32_bf16 v[62:65], v[146:149], v[178:181], v[62:65]
	v_mfma_f32_16x16x32_bf16 v[58:61], v[154:157], v[178:181], v[58:61]
	v_mfma_f32_16x16x32_bf16 v[46:49], v[146:149], v[186:189], v[46:49]
	v_mfma_f32_16x16x32_bf16 v[42:45], v[154:157], v[186:189], v[42:45]
	v_mfma_f32_16x16x32_bf16 v[30:33], v[146:149], v[204:207], v[30:33]
	v_mfma_f32_16x16x32_bf16 v[26:29], v[154:157], v[204:207], v[26:29]
	v_mfma_f32_16x16x32_bf16 v[14:17], v[146:149], v[212:215], v[14:17]
	v_mfma_f32_16x16x32_bf16 v[10:13], v[154:157], v[212:215], v[10:13]
	v_mfma_f32_16x16x32_bf16 v[62:65], v[150:153], v[182:185], v[62:65]
	v_mfma_f32_16x16x32_bf16 v[58:61], v[158:161], v[182:185], v[58:61]
	v_mfma_f32_16x16x32_bf16 v[46:49], v[150:153], v[190:193], v[46:49]
	v_mfma_f32_16x16x32_bf16 v[42:45], v[158:161], v[190:193], v[42:45]
	v_mfma_f32_16x16x32_bf16 v[30:33], v[150:153], v[208:211], v[30:33]
	v_mfma_f32_16x16x32_bf16 v[26:29], v[158:161], v[208:211], v[26:29]
	v_mfma_f32_16x16x32_bf16 v[14:17], v[150:153], v[216:219], v[14:17]
	v_mfma_f32_16x16x32_bf16 v[10:13], v[158:161], v[216:219], v[10:13]
	v_mfma_f32_16x16x32_bf16 v[54:57], v[162:165], v[178:181], v[54:57]
	v_mfma_f32_16x16x32_bf16 v[50:53], v[170:173], v[178:181], v[50:53]
	v_mfma_f32_16x16x32_bf16 v[38:41], v[162:165], v[186:189], v[38:41]
	v_mfma_f32_16x16x32_bf16 v[34:37], v[170:173], v[186:189], v[34:37]
	v_mfma_f32_16x16x32_bf16 v[22:25], v[162:165], v[204:207], v[22:25]
	v_mfma_f32_16x16x32_bf16 v[18:21], v[170:173], v[204:207], v[18:21]
	v_mfma_f32_16x16x32_bf16 v[6:9], v[162:165], v[212:215], v[6:9]
	v_mfma_f32_16x16x32_bf16 v[2:5], v[170:173], v[212:215], v[2:5]
	v_mfma_f32_16x16x32_bf16 v[54:57], v[166:169], v[182:185], v[54:57]
	v_mfma_f32_16x16x32_bf16 v[50:53], v[174:177], v[182:185], v[50:53]
	v_mfma_f32_16x16x32_bf16 v[38:41], v[166:169], v[190:193], v[38:41]
	v_mfma_f32_16x16x32_bf16 v[34:37], v[174:177], v[190:193], v[34:37]
	v_mfma_f32_16x16x32_bf16 v[22:25], v[166:169], v[208:211], v[22:25]
	v_mfma_f32_16x16x32_bf16 v[18:21], v[174:177], v[208:211], v[18:21]
	v_mfma_f32_16x16x32_bf16 v[6:9], v[166:169], v[216:219], v[6:9]
	v_mfma_f32_16x16x32_bf16 v[2:5], v[174:177], v[216:219], v[2:5]
	s_setprio 0
	s_barrier
	s_add_u32 s52, s52, 0x100
	s_addc_u32 s53, s53, 0
	s_add_u32 s12, s12, 0x100
	s_addc_u32 s13, s13, 0
	s_cmp_ge_i32 s24, s68
	s_mov_b32 s15, s24
	s_cbranch_scc0 .LBB0_353

; #define PG8_STAGE(bufoff, gbase, voff) do { _Pragma("unroll") for (int _i = 0; _i < 2; ++_i) \
;         __builtin_amdgcn_global_load_lds((const unsigned*)((const char*)(gbase) + (voff)[_i]), (PG8_LAS unsigned*)(lds + (bufoff) + ldsw + _i * 8192), 16, 0, 0); } while (0)
; #define PG8_LDA(dst, b, h) do { _Pragma("unroll") for (int m = 0; m < 4; ++m) _Pragma("unroll") for (int k = 0; k < 2; ++k) dst[m][k] = *(const PG8_LAS bf16x8*)(lds + PG8_SA(b, h) + aoff + m * 2048 + k * 1024); } while (0)
; #define PG8_LDB(dst, b, h) do { _Pragma("unroll") for (int n = 0; n < 2; ++n) _Pragma("unroll") for (int k = 0; k < 2; ++k) dst[n][k] = *(const PG8_LAS bf16x8*)(lds + PG8_SB(b, h) + boff + n * 2048 + k * 1024); } while (0)
; #define PG8_MMA(ai, bj, At, Bt) do { __builtin_amdgcn_s_setprio(1); _Pragma("unroll") for (int m = 0; m < 4; ++m) _Pragma("unroll") for (int n = 0; n < 2; ++n) _Pragma("unroll") for (int k = 0; k < 2; ++k) \
;         acc[ai][bj][m][n] = __builtin_amdgcn_mfma_f32_16x16x32_bf16(Bt[n][k], At[m][k], acc[ai][bj][m][n], 0, 0, 0); __builtin_amdgcn_s_setprio(0); } while (0)
; #define PG8_WAIT_V(n) asm volatile("s_waitcnt vmcnt(" #n ")" ::: "memory")
; #define PG8_BAR __builtin_amdgcn_s_barrier()
; template <class Epi, class Sched, bool ALIGN_EPI = false, bool SP2 = false>
; __device__ __forceinline__ void gemm_phase(PG8_LAS unsigned char* lds, const Gemm g, const Sched& S, const Epi& E, int tid_in) {
;     ...
;         for (int t = 0; t < nt; t += 2) {
;             const bool last = (t == nt - 2);
;             const char* a1 = cA + (size_t)(t + 1) * kstep;
;             const char* a2 = last ? nA : cA + (size_t)(t + 2) * kstep; const char* b2 = last ? nB : cB + (size_t)(t + 2) * kstep;
;             const char* a3 = a2 + kstep; const char* b3 = b2 + kstep;
;             if (last && has_next) S.a_ready(nxt);
;             if constexpr (SP2) {
;             PG8_LDB(B0, 0, 0); PG8_LDB(B1, 0, 1); PG8_SCHED; PG8_LDA(At, 0, 0); PG8_STAGE(PG8_SA(1, 1), a1 + hstepA, voffA);
;             PG8_WAIT_V(8); PG8_WAIT_L(0); PG8_BAR; PG8_MMA(0, 0, At, B0); PG8_MMA(0, 1, At, B1); PG8_BAR; PG8_SCHED;
;             PG8_LDA(At, 0, 1); PG8_STAGE(PG8_SB(0, 0), b2, voffB); PG8_STAGE(PG8_SB(0, 1), b2 + hstep, voffB); PG8_STAGE(PG8_SA(0, 0), a2, voffA);
;             PG8_WAIT_V(8); PG8_WAIT_L(0); PG8_BAR; PG8_MMA(1, 0, At, B0); PG8_MMA(1, 1, At, B1); PG8_BAR; PG8_SCHED;
.LBB0_413:
	s_add_i32 s62, s15, 2
	s_add_u32 s60, s58, 0x80
	s_addc_u32 s61, s59, 0
	s_add_i32 s63, 0, 0x10000
	s_cmp_eq_u32 s93, s15
	s_cselect_b32 s61, s1, s61
	s_cselect_b32 s60, s0, s60
	s_cselect_b32 s65, s75, s13
	s_cselect_b32 s64, s74, s12
	s_add_i32 s15, 0, 0x14000
	v_add_u32_e32 v142, s63, v206
	v_add_u32_e32 v146, s15, v206
	ds_read_b128 v[130:133], v142
	ds_read_b128 v[134:137], v142 offset:1024
	ds_read_b128 v[138:141], v142 offset:2048
	ds_read_b128 v[142:145], v142 offset:3072
	ds_read_b128 v[160:163], v146
	ds_read_b128 v[164:167], v146 offset:1024
	ds_read_b128 v[168:171], v146 offset:2048
	ds_read_b128 v[172:175], v146 offset:3072
	v_lshl_add_u64 v[146:147], s[58:59], 0, v[156:157]
	s_add_i32 m0, s78, 0xc000
	ds_read_b128 v[176:179], v222
	ds_read_b128 v[180:183], v222 offset:1024
	ds_read_b128 v[184:187], v222 offset:2048
	ds_read_b128 v[188:191], v222 offset:3072
	ds_read_b128 v[192:195], v222 offset:4096
	ds_read_b128 v[224:227], v222 offset:5120
	ds_read_b128 v[228:231], v222 offset:6144
	ds_read_b128 v[232:235], v222 offset:7168
	global_load_lds_dwordx4 v[146:147], off
	v_lshl_add_u64 v[146:147], s[58:59], 0, v[158:159]
	s_add_i32 m0, s78, 0xe000
	s_nop 0
	global_load_lds_dwordx4 v[146:147], off
	s_waitcnt vmcnt(8)
	s_waitcnt lgkmcnt(0)
	s_barrier
	s_setprio 1
	s_waitcnt lgkmcnt(0)
	v_mfma_f32_16x16x32_bf16 v[126:129], v[130:133], v[176:179], v[126:129]
	v_mfma_f32_16x16x32_bf16 v[122:125], v[138:141], v[176:179], v[122:125]
	v_mfma_f32_16x16x32_bf16 v[102:105], v[130:133], v[184:187], v[102:105]
	v_mfma_f32_16x16x32_bf16 v[70:73], v[138:141], v[184:187], v[70:73]
	v_mfma_f32_16x16x32_bf16 v[98:101], v[130:133], v[192:195], v[98:101]
	v_mfma_f32_16x16x32_bf16 v[66:69], v[138:141], v[192:195], v[66:69]
	v_mfma_f32_16x16x32_bf16 v[118:121], v[130:133], v[228:231], v[118:121]
	v_mfma_f32_16x16x32_bf16 v[114:117], v[138:141], v[228:231], v[114:117]
	v_mfma_f32_16x16x32_bf16 v[126:129], v[134:137], v[180:183], v[126:129]
	v_mfma_f32_16x16x32_bf16 v[122:125], v[142:145], v[180:183], v[122:125]
	v_mfma_f32_16x16x32_bf16 v[102:105], v[134:137], v[188:191], v[102:105]
	v_mfma_f32_16x16x32_bf16 v[70:73], v[142:145], v[188:191], v[70:73]
	v_mfma_f32_16x16x32_bf16 v[98:101], v[134:137], v[224:227], v[98:101]
	v_mfma_f32_16x16x32_bf16 v[66:69], v[142:145], v[224:227], v[66:69]
	v_mfma_f32_16x16x32_bf16 v[118:121], v[134:137], v[232:235], v[118:121]
	v_mfma_f32_16x16x32_bf16 v[114:117], v[142:145], v[232:235], v[114:117]
	v_mfma_f32_16x16x32_bf16 v[94:97], v[160:163], v[176:179], v[94:97]
	v_mfma_f32_16x16x32_bf16 v[62:65], v[168:171], v[176:179], v[62:65]
	v_mfma_f32_16x16x32_bf16 v[86:89], v[160:163], v[184:187], v[86:89]
	v_mfma_f32_16x16x32_bf16 v[58:61], v[168:171], v[184:187], v[58:61]
	v_mfma_f32_16x16x32_bf16 v[82:85], v[160:163], v[192:195], v[82:85]
	v_mfma_f32_16x16x32_bf16 v[54:57], v[168:171], v[192:195], v[54:57]
	v_mfma_f32_16x16x32_bf16 v[78:81], v[160:163], v[228:231], v[78:81]
	v_mfma_f32_16x16x32_bf16 v[50:53], v[168:171], v[228:231], v[50:53]
	v_mfma_f32_16x16x32_bf16 v[94:97], v[164:167], v[180:183], v[94:97]
	v_mfma_f32_16x16x32_bf16 v[62:65], v[172:175], v[180:183], v[62:65]
	v_mfma_f32_16x16x32_bf16 v[86:89], v[164:167], v[188:191], v[86:89]
	v_mfma_f32_16x16x32_bf16 v[58:61], v[172:175], v[188:191], v[58:61]
	v_mfma_f32_16x16x32_bf16 v[82:85], v[164:167], v[224:227], v[82:85]
	v_mfma_f32_16x16x32_bf16 v[54:57], v[172:175], v[224:227], v[54:57]
	v_mfma_f32_16x16x32_bf16 v[78:81], v[164:167], v[232:235], v[78:81]
	v_mfma_f32_16x16x32_bf16 v[50:53], v[172:175], v[232:235], v[50:53]
	s_setprio 0
	s_barrier
	s_add_i32 s63, s63, s91
	v_lshl_add_u64 v[146:147], s[64:65], 0, v[0:1]
	s_mov_b32 m0, s63
	ds_read_b128 v[176:179], v222 offset:16384
	ds_read_b128 v[180:183], v222 offset:17408
	ds_read_b128 v[184:187], v222 offset:18432
	ds_read_b128 v[188:191], v222 offset:19456
	ds_read_b128 v[192:195], v222 offset:20480
	ds_read_b128 v[224:227], v222 offset:21504
	ds_read_b128 v[228:231], v222 offset:22528
	ds_read_b128 v[232:235], v222 offset:23552
	global_load_lds_dwordx4 v[146:147], off
	s_add_i32 m0, s63, 0x2000
	v_lshl_add_u64 v[236:237], s[64:65], 0, v[152:153]
	s_add_u32 s64, s64, s18
	s_addc_u32 s65, s65, s19
	s_add_i32 s15, s15, s91
	global_load_lds_dwordx4 v[236:237], off
	v_lshl_add_u64 v[238:239], s[64:65], 0, v[0:1]
	s_mov_b32 m0, s15
	v_lshl_add_u64 v[240:241], s[64:65], 0, v[152:153]
	global_load_lds_dwordx4 v[238:239], off
	s_add_i32 m0, s15, 0x2000
	v_lshl_add_u64 v[242:243], s[60:61], 0, v[148:149]
	global_load_lds_dwordx4 v[240:241], off
	s_mov_b32 m0, s78
	v_lshl_add_u64 v[244:245], s[60:61], 0, v[150:151]
	global_load_lds_dwordx4 v[242:243], off
	s_mov_b32 m0, s79
	s_nop 0
	global_load_lds_dwordx4 v[244:245], off
	s_waitcnt vmcnt(8)
	s_waitcnt lgkmcnt(0)
	s_barrier
; #define PG8_STAGE(bufoff, gbase, voff) do { _Pragma("unroll") for (int _i = 0; _i < 2; ++_i) \
;         __builtin_amdgcn_global_load_lds((const unsigned*)((const char*)(gbase) + (voff)[_i]), (PG8_LAS unsigned*)(lds + (bufoff) + ldsw + _i * 8192), 16, 0, 0); } while (0)
; #define PG8_LDA(dst, b, h) do { _Pragma("unroll") for (int m = 0; m < 4; ++m) _Pragma("unroll") for (int k = 0; k < 2; ++k) dst[m][k] = *(const PG8_LAS bf16x8*)(lds + PG8_SA(b, h) + aoff + m * 2048 + k * 1024); } while (0)
; #define PG8_LDB(dst, b, h) do { _Pragma("unroll") for (int n = 0; n < 2; ++n) _Pragma("unroll") for (int k = 0; k < 2; ++k) dst[n][k] = *(const PG8_LAS bf16x8*)(lds + PG8_SB(b, h) + boff + n * 2048 + k * 1024); } while (0)
; #define PG8_MMA(ai, bj, At, Bt) do { __builtin_amdgcn_s_setprio(1); _Pragma("unroll") for (int m = 0; m < 4; ++m) _Pragma("unroll") for (int n = 0; n < 2; ++n) _Pragma("unroll") for (int k = 0; k < 2; ++k) \
;         acc[ai][bj][m][n] = __builtin_amdgcn_mfma_f32_16x16x32_bf16(Bt[n][k], At[m][k], acc[ai][bj][m][n], 0, 0, 0); __builtin_amdgcn_s_setprio(0); } while (0)
; #define PG8_WAIT_V(n) asm volatile("s_waitcnt vmcnt(" #n ")" ::: "memory")
; #define PG8_WAIT_L(n) asm volatile("s_waitcnt lgkmcnt(" #n ")" ::: "memory")
; #define PG8_BAR __builtin_amdgcn_s_barrier()
; #define PG8_SCHED __builtin_amdgcn_sched_barrier(0)
; template <class Epi, class Sched, bool ALIGN_EPI = false, bool SP2 = false>
; __device__ __forceinline__ void gemm_phase(PG8_LAS unsigned char* lds, const Gemm g, const Sched& S, const Epi& E, int tid_in) {
;     ...
;             PG8_WAIT_V(8); PG8_WAIT_L(0); PG8_BAR; PG8_MMA(1, 0, At, B0); PG8_MMA(1, 1, At, B1); PG8_BAR; PG8_SCHED;
;             PG8_LDB(B0, 1, 0); PG8_LDB(B1, 1, 1); PG8_SCHED; PG8_LDA(At, 1, 0); PG8_STAGE(PG8_SA(0, 1), a2 + hstepA, voffA);
;             PG8_WAIT_V(8); PG8_WAIT_L(0); PG8_BAR; PG8_MMA(0, 0, At, B0); PG8_MMA(0, 1, At, B1); PG8_BAR; PG8_SCHED;
	s_setprio 1
	s_waitcnt lgkmcnt(0)
	v_mfma_f32_16x16x32_bf16 v[110:113], v[130:133], v[176:179], v[110:113]
	v_mfma_f32_16x16x32_bf16 v[90:93], v[138:141], v[176:179], v[90:93]
	v_mfma_f32_16x16x32_bf16 v[46:49], v[130:133], v[184:187], v[46:49]
	v_mfma_f32_16x16x32_bf16 v[22:25], v[138:141], v[184:187], v[22:25]
	v_mfma_f32_16x16x32_bf16 v[42:45], v[130:133], v[192:195], v[42:45]
	v_mfma_f32_16x16x32_bf16 v[18:21], v[138:141], v[192:195], v[18:21]
	v_mfma_f32_16x16x32_bf16 v[106:109], v[130:133], v[228:231], v[106:109]
	v_mfma_f32_16x16x32_bf16 v[74:77], v[138:141], v[228:231], v[74:77]
	v_mfma_f32_16x16x32_bf16 v[110:113], v[134:137], v[180:183], v[110:113]
	v_mfma_f32_16x16x32_bf16 v[90:93], v[142:145], v[180:183], v[90:93]
	v_mfma_f32_16x16x32_bf16 v[46:49], v[134:137], v[188:191], v[46:49]
	v_mfma_f32_16x16x32_bf16 v[22:25], v[142:145], v[188:191], v[22:25]
	v_mfma_f32_16x16x32_bf16 v[42:45], v[134:137], v[224:227], v[42:45]
	v_mfma_f32_16x16x32_bf16 v[18:21], v[142:145], v[224:227], v[18:21]
	v_mfma_f32_16x16x32_bf16 v[106:109], v[134:137], v[232:235], v[106:109]
	v_mfma_f32_16x16x32_bf16 v[74:77], v[142:145], v[232:235], v[74:77]
	v_mfma_f32_16x16x32_bf16 v[38:41], v[160:163], v[176:179], v[38:41]
	v_mfma_f32_16x16x32_bf16 v[14:17], v[168:171], v[176:179], v[14:17]
	v_mfma_f32_16x16x32_bf16 v[34:37], v[160:163], v[184:187], v[34:37]
	v_mfma_f32_16x16x32_bf16 v[10:13], v[168:171], v[184:187], v[10:13]
	v_mfma_f32_16x16x32_bf16 v[30:33], v[160:163], v[192:195], v[30:33]
	v_mfma_f32_16x16x32_bf16 v[6:9], v[168:171], v[192:195], v[6:9]
	v_mfma_f32_16x16x32_bf16 v[26:29], v[160:163], v[228:231], v[26:29]
	v_mfma_f32_16x16x32_bf16 v[2:5], v[168:171], v[228:231], v[2:5]
	v_mfma_f32_16x16x32_bf16 v[38:41], v[164:167], v[180:183], v[38:41]
	v_mfma_f32_16x16x32_bf16 v[14:17], v[172:175], v[180:183], v[14:17]
	v_mfma_f32_16x16x32_bf16 v[34:37], v[164:167], v[188:191], v[34:37]
	v_mfma_f32_16x16x32_bf16 v[10:13], v[172:175], v[188:191], v[10:13]
	v_mfma_f32_16x16x32_bf16 v[30:33], v[164:167], v[224:227], v[30:33]
	v_mfma_f32_16x16x32_bf16 v[6:9], v[172:175], v[224:227], v[6:9]
	v_mfma_f32_16x16x32_bf16 v[26:29], v[164:167], v[232:235], v[26:29]
	v_mfma_f32_16x16x32_bf16 v[2:5], v[172:175], v[232:235], v[2:5]
	s_setprio 0
	s_barrier
	s_add_i32 s15, 0, 0x18000
	s_add_i32 s63, 0, 0x1c000
	v_add_u32_e32 v142, s15, v206
	v_add_u32_e32 v172, s63, v206
	ds_read_b128 v[130:133], v142
	ds_read_b128 v[134:137], v142 offset:1024
	ds_read_b128 v[138:141], v142 offset:2048
	ds_read_b128 v[142:145], v142 offset:3072
	ds_read_b128 v[160:163], v172
	ds_read_b128 v[164:167], v172 offset:1024
	ds_read_b128 v[168:171], v172 offset:2048
	ds_read_b128 v[172:175], v172 offset:3072
	s_add_u32 s60, s60, s18
	s_addc_u32 s61, s61, s19
	s_mov_b32 m0, s80
	v_lshl_add_u64 v[246:247], s[60:61], 0, v[148:149]
	ds_read_b128 v[176:179], v222 offset:32768
	ds_read_b128 v[180:183], v222 offset:33792
	ds_read_b128 v[184:187], v222 offset:34816
	ds_read_b128 v[188:191], v222 offset:35840
	ds_read_b128 v[192:195], v222 offset:36864
	ds_read_b128 v[224:227], v222 offset:37888
	ds_read_b128 v[228:231], v222 offset:38912
	ds_read_b128 v[232:235], v222 offset:39936
	global_load_lds_dwordx4 v[246:247], off
	v_lshl_add_u64 v[246:247], s[60:61], 0, v[150:151]
	s_mov_b32 m0, s81
	s_nop 0
	global_load_lds_dwordx4 v[246:247], off
	s_waitcnt vmcnt(8)
	s_waitcnt lgkmcnt(0)
	s_barrier
	s_setprio 1
	s_waitcnt lgkmcnt(0)
	v_mfma_f32_16x16x32_bf16 v[126:129], v[130:133], v[176:179], v[126:129]
	v_mfma_f32_16x16x32_bf16 v[122:125], v[138:141], v[176:179], v[122:125]
	v_mfma_f32_16x16x32_bf16 v[102:105], v[130:133], v[184:187], v[102:105]
	v_mfma_f32_16x16x32_bf16 v[70:73], v[138:141], v[184:187], v[70:73]
	v_mfma_f32_16x16x32_bf16 v[98:101], v[130:133], v[192:195], v[98:101]
	v_mfma_f32_16x16x32_bf16 v[66:69], v[138:141], v[192:195], v[66:69]
	v_mfma_f32_16x16x32_bf16 v[118:121], v[130:133], v[228:231], v[118:121]
	v_mfma_f32_16x16x32_bf16 v[114:117], v[138:141], v[228:231], v[114:117]
	v_mfma_f32_16x16x32_bf16 v[126:129], v[134:137], v[180:183], v[126:129]
	v_mfma_f32_16x16x32_bf16 v[122:125], v[142:145], v[180:183], v[122:125]
	v_mfma_f32_16x16x32_bf16 v[102:105], v[134:137], v[188:191], v[102:105]
	v_mfma_f32_16x16x32_bf16 v[70:73], v[142:145], v[188:191], v[70:73]
	v_mfma_f32_16x16x32_bf16 v[98:101], v[134:137], v[224:227], v[98:101]
	v_mfma_f32_16x16x32_bf16 v[66:69], v[142:145], v[224:227], v[66:69]
	v_mfma_f32_16x16x32_bf16 v[118:121], v[134:137], v[232:235], v[118:121]
	v_mfma_f32_16x16x32_bf16 v[114:117], v[142:145], v[232:235], v[114:117]
	v_mfma_f32_16x16x32_bf16 v[94:97], v[160:163], v[176:179], v[94:97]
	v_mfma_f32_16x16x32_bf16 v[62:65], v[168:171], v[176:179], v[62:65]
	v_mfma_f32_16x16x32_bf16 v[86:89], v[160:163], v[184:187], v[86:89]
	v_mfma_f32_16x16x32_bf16 v[58:61], v[168:171], v[184:187], v[58:61]
	v_mfma_f32_16x16x32_bf16 v[82:85], v[160:163], v[192:195], v[82:85]
	v_mfma_f32_16x16x32_bf16 v[54:57], v[168:171], v[192:195], v[54:57]
	v_mfma_f32_16x16x32_bf16 v[78:81], v[160:163], v[228:231], v[78:81]
	v_mfma_f32_16x16x32_bf16 v[50:53], v[168:171], v[228:231], v[50:53]
	v_mfma_f32_16x16x32_bf16 v[94:97], v[164:167], v[180:183], v[94:97]
	v_mfma_f32_16x16x32_bf16 v[62:65], v[172:175], v[180:183], v[62:65]
	v_mfma_f32_16x16x32_bf16 v[86:89], v[164:167], v[188:191], v[86:89]
	v_mfma_f32_16x16x32_bf16 v[58:61], v[172:175], v[188:191], v[58:61]
	v_mfma_f32_16x16x32_bf16 v[82:85], v[164:167], v[224:227], v[82:85]
	v_mfma_f32_16x16x32_bf16 v[54:57], v[172:175], v[224:227], v[54:57]
	v_mfma_f32_16x16x32_bf16 v[78:81], v[164:167], v[232:235], v[78:81]
	v_mfma_f32_16x16x32_bf16 v[50:53], v[172:175], v[232:235], v[50:53]
	s_setprio 0
	s_barrier
; #define PG8_STAGE(bufoff, gbase, voff) do { _Pragma("unroll") for (int _i = 0; _i < 2; ++_i) \
;         __builtin_amdgcn_global_load_lds((const unsigned*)((const char*)(gbase) + (voff)[_i]), (PG8_LAS unsigned*)(lds + (bufoff) + ldsw + _i * 8192), 16, 0, 0); } while (0)
; #define PG8_LDA(dst, b, h) do { _Pragma("unroll") for (int m = 0; m < 4; ++m) _Pragma("unroll") for (int k = 0; k < 2; ++k) dst[m][k] = *(const PG8_LAS bf16x8*)(lds + PG8_SA(b, h) + aoff + m * 2048 + k * 1024); } while (0)
; #define PG8_MMA(ai, bj, At, Bt) do { __builtin_amdgcn_s_setprio(1); _Pragma("unroll") for (int m = 0; m < 4; ++m) _Pragma("unroll") for (int n = 0; n < 2; ++n) _Pragma("unroll") for (int k = 0; k < 2; ++k) \
;         acc[ai][bj][m][n] = __builtin_amdgcn_mfma_f32_16x16x32_bf16(Bt[n][k], At[m][k], acc[ai][bj][m][n], 0, 0, 0); __builtin_amdgcn_s_setprio(0); } while (0)
; #define PG8_WAIT_V(n) asm volatile("s_waitcnt vmcnt(" #n ")" ::: "memory")
; #define PG8_WAIT_L(n) asm volatile("s_waitcnt lgkmcnt(" #n ")" ::: "memory")
; #define PG8_BAR __builtin_amdgcn_s_barrier()
; #define PG8_SCHED __builtin_amdgcn_sched_barrier(0)
; template <class Epi, class Sched, bool ALIGN_EPI = false, bool SP2 = false>
; __device__ __forceinline__ void gemm_phase(PG8_LAS unsigned char* lds, const Gemm g, const Sched& S, const Epi& E, int tid_in) {
;     ...
;             PG8_LDA(At, 1, 1); PG8_STAGE(PG8_SB(1, 0), b3, voffB); PG8_STAGE(PG8_SB(1, 1), b3 + hstep, voffB); PG8_STAGE(PG8_SA(1, 0), a3, voffA);
;             PG8_WAIT_V(8); PG8_WAIT_L(0); PG8_BAR; PG8_MMA(1, 0, At, B0); PG8_MMA(1, 1, At, B1); PG8_BAR; PG8_SCHED;
	s_add_i32 s15, s15, s91
	v_lshl_add_u64 v[146:147], v[146:147], 0, s[28:29]
	s_mov_b32 m0, s15
	ds_read_b128 v[176:179], v222 offset:49152
	ds_read_b128 v[180:183], v222 offset:50176
	ds_read_b128 v[184:187], v222 offset:51200
	ds_read_b128 v[188:191], v222 offset:52224
	ds_read_b128 v[192:195], v222 offset:53248
	ds_read_b128 v[224:227], v222 offset:54272
	ds_read_b128 v[228:231], v222 offset:55296
	ds_read_b128 v[232:235], v222 offset:56320
	global_load_lds_dwordx4 v[146:147], off
	v_lshl_add_u64 v[146:147], v[236:237], 0, s[28:29]
	s_add_i32 m0, s15, 0x2000
	s_add_i32 s15, s63, s91
	global_load_lds_dwordx4 v[146:147], off
	v_lshl_add_u64 v[146:147], v[238:239], 0, s[28:29]
	s_mov_b32 m0, s15
	s_nop 0
	global_load_lds_dwordx4 v[146:147], off
	v_lshl_add_u64 v[146:147], v[240:241], 0, s[28:29]
	s_add_i32 m0, s15, 0x2000
	s_nop 0
	global_load_lds_dwordx4 v[146:147], off
	v_lshl_add_u64 v[146:147], v[242:243], 0, s[28:29]
	s_mov_b32 m0, s11
	s_nop 0
	global_load_lds_dwordx4 v[146:147], off
	v_lshl_add_u64 v[146:147], v[244:245], 0, s[28:29]
	s_mov_b32 m0, s92
	s_nop 0
	global_load_lds_dwordx4 v[146:147], off
	s_waitcnt vmcnt(8)
	s_waitcnt lgkmcnt(0)
	s_barrier
	s_setprio 1
	s_waitcnt lgkmcnt(0)
	v_mfma_f32_16x16x32_bf16 v[110:113], v[130:133], v[176:179], v[110:113]
	v_mfma_f32_16x16x32_bf16 v[90:93], v[138:141], v[176:179], v[90:93]
	v_mfma_f32_16x16x32_bf16 v[46:49], v[130:133], v[184:187], v[46:49]
	v_mfma_f32_16x16x32_bf16 v[22:25], v[138:141], v[184:187], v[22:25]
	v_mfma_f32_16x16x32_bf16 v[42:45], v[130:133], v[192:195], v[42:45]
	v_mfma_f32_16x16x32_bf16 v[18:21], v[138:141], v[192:195], v[18:21]
	v_mfma_f32_16x16x32_bf16 v[106:109], v[130:133], v[228:231], v[106:109]
	v_mfma_f32_16x16x32_bf16 v[74:77], v[138:141], v[228:231], v[74:77]
	v_mfma_f32_16x16x32_bf16 v[110:113], v[134:137], v[180:183], v[110:113]
	v_mfma_f32_16x16x32_bf16 v[90:93], v[142:145], v[180:183], v[90:93]
	v_mfma_f32_16x16x32_bf16 v[46:49], v[134:137], v[188:191], v[46:49]
	v_mfma_f32_16x16x32_bf16 v[22:25], v[142:145], v[188:191], v[22:25]
	v_mfma_f32_16x16x32_bf16 v[42:45], v[134:137], v[224:227], v[42:45]
	v_mfma_f32_16x16x32_bf16 v[18:21], v[142:145], v[224:227], v[18:21]
	v_mfma_f32_16x16x32_bf16 v[106:109], v[134:137], v[232:235], v[106:109]
	v_mfma_f32_16x16x32_bf16 v[74:77], v[142:145], v[232:235], v[74:77]
	v_mfma_f32_16x16x32_bf16 v[38:41], v[160:163], v[176:179], v[38:41]
	v_mfma_f32_16x16x32_bf16 v[14:17], v[168:171], v[176:179], v[14:17]
	v_mfma_f32_16x16x32_bf16 v[34:37], v[160:163], v[184:187], v[34:37]
	v_mfma_f32_16x16x32_bf16 v[10:13], v[168:171], v[184:187], v[10:13]
	v_mfma_f32_16x16x32_bf16 v[30:33], v[160:163], v[192:195], v[30:33]
	v_mfma_f32_16x16x32_bf16 v[6:9], v[168:171], v[192:195], v[6:9]
	v_mfma_f32_16x16x32_bf16 v[26:29], v[160:163], v[228:231], v[26:29]
	v_mfma_f32_16x16x32_bf16 v[2:5], v[168:171], v[228:231], v[2:5]
	v_mfma_f32_16x16x32_bf16 v[38:41], v[164:167], v[180:183], v[38:41]
	v_mfma_f32_16x16x32_bf16 v[14:17], v[172:175], v[180:183], v[14:17]
	v_mfma_f32_16x16x32_bf16 v[34:37], v[164:167], v[188:191], v[34:37]
	v_mfma_f32_16x16x32_bf16 v[10:13], v[172:175], v[188:191], v[10:13]
	v_mfma_f32_16x16x32_bf16 v[30:33], v[164:167], v[224:227], v[30:33]
	v_mfma_f32_16x16x32_bf16 v[6:9], v[172:175], v[224:227], v[6:9]
	v_mfma_f32_16x16x32_bf16 v[26:29], v[164:167], v[232:235], v[26:29]
	v_mfma_f32_16x16x32_bf16 v[2:5], v[172:175], v[232:235], v[2:5]
	s_setprio 0
	s_barrier
	s_add_u32 s58, s58, 0x100
	s_addc_u32 s59, s59, 0
	s_add_u32 s12, s12, 0x100
	s_addc_u32 s13, s13, 0
	s_cmp_ge_i32 s62, s10
	s_mov_b32 s15, s62
	s_cbranch_scc0 .LBB0_413

; #define PG8_STAGE(bufoff, gbase, voff) do { _Pragma("unroll") for (int _i = 0; _i < 2; ++_i) \
;         __builtin_amdgcn_global_load_lds((const unsigned*)((const char*)(gbase) + (voff)[_i]), (PG8_LAS unsigned*)(lds + (bufoff) + ldsw + _i * 8192), 16, 0, 0); } while (0)
; #define PG8_LDA(dst, b, h) do { _Pragma("unroll") for (int m = 0; m < 4; ++m) _Pragma("unroll") for (int k = 0; k < 2; ++k) dst[m][k] = *(const PG8_LAS bf16x8*)(lds + PG8_SA(b, h) + aoff + m * 2048 + k * 1024); } while (0)
; #define PG8_LDB(dst, b, h) do { _Pragma("unroll") for (int n = 0; n < 2; ++n) _Pragma("unroll") for (int k = 0; k < 2; ++k) dst[n][k] = *(const PG8_LAS bf16x8*)(lds + PG8_SB(b, h) + boff + n * 2048 + k * 1024); } while (0)
; #define PG8_MMA(ai, bj, At, Bt) do { __builtin_amdgcn_s_setprio(1); _Pragma("unroll") for (int m = 0; m < 4; ++m) _Pragma("unroll") for (int n = 0; n < 2; ++n) _Pragma("unroll") for (int k = 0; k < 2; ++k) \
;         acc[ai][bj][m][n] = __builtin_amdgcn_mfma_f32_16x16x32_bf16(Bt[n][k], At[m][k], acc[ai][bj][m][n], 0, 0, 0); __builtin_amdgcn_s_setprio(0); } while (0)
; #define PG8_WAIT_V(n) asm volatile("s_waitcnt vmcnt(" #n ")" ::: "memory")
; #define PG8_BAR __builtin_amdgcn_s_barrier()
; template <class Epi, class Sched, bool ALIGN_EPI = false, bool SP2 = false>
; __device__ __forceinline__ void gemm_phase(PG8_LAS unsigned char* lds, const Gemm g, const Sched& S, const Epi& E, int tid_in) {
;     ...
;         for (int t = 0; t < nt; t += 2) {
;             const bool last = (t == nt - 2);
;             const char* a1 = cA + (size_t)(t + 1) * kstep;
;             const char* a2 = last ? nA : cA + (size_t)(t + 2) * kstep; const char* b2 = last ? nB : cB + (size_t)(t + 2) * kstep;
;             const char* a3 = a2 + kstep; const char* b3 = b2 + kstep;
;             if (last && has_next) S.a_ready(nxt);
;             if constexpr (SP2) {
;             PG8_LDB(B0, 0, 0); PG8_LDB(B1, 0, 1); PG8_SCHED; PG8_LDA(At, 0, 0); PG8_STAGE(PG8_SA(1, 1), a1 + hstepA, voffA);
;             PG8_WAIT_V(8); PG8_WAIT_L(0); PG8_BAR; PG8_MMA(0, 0, At, B0); PG8_MMA(0, 1, At, B1); PG8_BAR; PG8_SCHED;
;             PG8_LDA(At, 0, 1); PG8_STAGE(PG8_SB(0, 0), b2, voffB); PG8_STAGE(PG8_SB(0, 1), b2 + hstep, voffB); PG8_STAGE(PG8_SA(0, 0), a2, voffA);
;             PG8_WAIT_V(8); PG8_WAIT_L(0); PG8_BAR; PG8_MMA(1, 0, At, B0); PG8_MMA(1, 1, At, B1); PG8_BAR; PG8_SCHED;
.LBB0_542:
	s_add_i32 s57, s15, 2
	s_add_u32 s54, s52, 0x80
	s_addc_u32 s55, s53, 0
	s_add_i32 s81, 0, 0x10000
	s_cmp_eq_u32 s70, s15
	s_cselect_b32 s55, s41, s55
	s_cselect_b32 s54, s40, s54
	v_add_u32_e32 v148, s81, v151
	s_cselect_b32 s59, s51, s13
	s_cselect_b32 s58, s50, s12
	s_add_i32 s15, 0, 0x14000
	ds_read_b128 v[140:143], v148
	ds_read_b128 v[144:147], v148 offset:1024
	ds_read_b128 v[154:157], v148 offset:2048
	ds_read_b128 v[158:161], v148 offset:3072
	v_add_u32_e32 v148, s15, v151
	ds_read_b128 v[162:165], v148
	ds_read_b128 v[166:169], v148 offset:1024
	ds_read_b128 v[170:173], v148 offset:2048
	ds_read_b128 v[174:177], v148 offset:3072
	v_lshl_add_u64 v[148:149], s[52:53], 0, v[136:137]
	s_add_i32 m0, s62, 0xc000
	ds_read_b128 v[178:181], v153
	ds_read_b128 v[182:185], v153 offset:1024
	ds_read_b128 v[186:189], v153 offset:2048
	ds_read_b128 v[190:193], v153 offset:3072
	ds_read_b128 v[204:207], v153 offset:4096
	ds_read_b128 v[208:211], v153 offset:5120
	ds_read_b128 v[212:215], v153 offset:6144
	ds_read_b128 v[216:219], v153 offset:7168
	global_load_lds_dwordx4 v[148:149], off
	v_lshl_add_u64 v[148:149], s[52:53], 0, v[138:139]
	s_add_i32 m0, s62, 0xe000
	s_nop 0
	global_load_lds_dwordx4 v[148:149], off
	s_waitcnt vmcnt(8)
	s_waitcnt lgkmcnt(0)
	s_barrier
	s_setprio 1
	s_waitcnt lgkmcnt(0)
	v_mfma_f32_16x16x32_bf16 v[126:129], v[140:143], v[178:181], v[126:129]
	v_mfma_f32_16x16x32_bf16 v[122:125], v[154:157], v[178:181], v[122:125]
	v_mfma_f32_16x16x32_bf16 v[110:113], v[140:143], v[186:189], v[110:113]
	v_mfma_f32_16x16x32_bf16 v[106:109], v[154:157], v[186:189], v[106:109]
	v_mfma_f32_16x16x32_bf16 v[94:97], v[140:143], v[204:207], v[94:97]
	v_mfma_f32_16x16x32_bf16 v[90:93], v[154:157], v[204:207], v[90:93]
	v_mfma_f32_16x16x32_bf16 v[78:81], v[140:143], v[212:215], v[78:81]
	v_mfma_f32_16x16x32_bf16 v[74:77], v[154:157], v[212:215], v[74:77]
	v_mfma_f32_16x16x32_bf16 v[126:129], v[144:147], v[182:185], v[126:129]
	v_mfma_f32_16x16x32_bf16 v[122:125], v[158:161], v[182:185], v[122:125]
	v_mfma_f32_16x16x32_bf16 v[110:113], v[144:147], v[190:193], v[110:113]
	v_mfma_f32_16x16x32_bf16 v[106:109], v[158:161], v[190:193], v[106:109]
	v_mfma_f32_16x16x32_bf16 v[94:97], v[144:147], v[208:211], v[94:97]
	v_mfma_f32_16x16x32_bf16 v[90:93], v[158:161], v[208:211], v[90:93]
	v_mfma_f32_16x16x32_bf16 v[78:81], v[144:147], v[216:219], v[78:81]
	v_mfma_f32_16x16x32_bf16 v[74:77], v[158:161], v[216:219], v[74:77]
	v_mfma_f32_16x16x32_bf16 v[118:121], v[162:165], v[178:181], v[118:121]
	v_mfma_f32_16x16x32_bf16 v[114:117], v[170:173], v[178:181], v[114:117]
	v_mfma_f32_16x16x32_bf16 v[102:105], v[162:165], v[186:189], v[102:105]
	v_mfma_f32_16x16x32_bf16 v[98:101], v[170:173], v[186:189], v[98:101]
	v_mfma_f32_16x16x32_bf16 v[86:89], v[162:165], v[204:207], v[86:89]
	v_mfma_f32_16x16x32_bf16 v[82:85], v[170:173], v[204:207], v[82:85]
	v_mfma_f32_16x16x32_bf16 v[70:73], v[162:165], v[212:215], v[70:73]
	v_mfma_f32_16x16x32_bf16 v[66:69], v[170:173], v[212:215], v[66:69]
	v_mfma_f32_16x16x32_bf16 v[118:121], v[166:169], v[182:185], v[118:121]
	v_mfma_f32_16x16x32_bf16 v[114:117], v[174:177], v[182:185], v[114:117]
	v_mfma_f32_16x16x32_bf16 v[102:105], v[166:169], v[190:193], v[102:105]
	v_mfma_f32_16x16x32_bf16 v[98:101], v[174:177], v[190:193], v[98:101]
	v_mfma_f32_16x16x32_bf16 v[86:89], v[166:169], v[208:211], v[86:89]
	v_mfma_f32_16x16x32_bf16 v[82:85], v[174:177], v[208:211], v[82:85]
	v_mfma_f32_16x16x32_bf16 v[70:73], v[166:169], v[216:219], v[70:73]
	v_mfma_f32_16x16x32_bf16 v[66:69], v[174:177], v[216:219], v[66:69]
	s_setprio 0
	s_barrier
	s_add_i32 s81, s81, s2
	v_lshl_add_u64 v[148:149], s[58:59], 0, v[0:1]
	s_mov_b32 m0, s81
	ds_read_b128 v[178:181], v153 offset:16384
	ds_read_b128 v[182:185], v153 offset:17408
	ds_read_b128 v[186:189], v153 offset:18432
	ds_read_b128 v[190:193], v153 offset:19456
	ds_read_b128 v[204:207], v153 offset:20480
	ds_read_b128 v[208:211], v153 offset:21504
	ds_read_b128 v[212:215], v153 offset:22528
	ds_read_b128 v[216:219], v153 offset:23552
	global_load_lds_dwordx4 v[148:149], off
	s_add_i32 m0, s81, 0x2000
	v_lshl_add_u64 v[194:195], s[58:59], 0, v[134:135]
	s_add_u32 s58, s58, s22
	s_addc_u32 s59, s59, s23
	s_add_i32 s15, s15, s2
	global_load_lds_dwordx4 v[194:195], off
	v_lshl_add_u64 v[220:221], s[58:59], 0, v[0:1]
	s_mov_b32 m0, s15
	v_lshl_add_u64 v[222:223], s[58:59], 0, v[134:135]
	global_load_lds_dwordx4 v[220:221], off
	s_add_i32 m0, s15, 0x2000
	v_lshl_add_u64 v[224:225], s[54:55], 0, v[130:131]
	global_load_lds_dwordx4 v[222:223], off
	s_mov_b32 m0, s62
	v_lshl_add_u64 v[226:227], s[54:55], 0, v[132:133]
	global_load_lds_dwordx4 v[224:225], off
	s_mov_b32 m0, s63
	s_nop 0
	global_load_lds_dwordx4 v[226:227], off
	s_waitcnt vmcnt(8)
	s_waitcnt lgkmcnt(0)
	s_barrier
; #define PG8_STAGE(bufoff, gbase, voff) do { _Pragma("unroll") for (int _i = 0; _i < 2; ++_i) \
;         __builtin_amdgcn_global_load_lds((const unsigned*)((const char*)(gbase) + (voff)[_i]), (PG8_LAS unsigned*)(lds + (bufoff) + ldsw + _i * 8192), 16, 0, 0); } while (0)
; #define PG8_LDA(dst, b, h) do { _Pragma("unroll") for (int m = 0; m < 4; ++m) _Pragma("unroll") for (int k = 0; k < 2; ++k) dst[m][k] = *(const PG8_LAS bf16x8*)(lds + PG8_SA(b, h) + aoff + m * 2048 + k * 1024); } while (0)
; #define PG8_LDB(dst, b, h) do { _Pragma("unroll") for (int n = 0; n < 2; ++n) _Pragma("unroll") for (int k = 0; k < 2; ++k) dst[n][k] = *(const PG8_LAS bf16x8*)(lds + PG8_SB(b, h) + boff + n * 2048 + k * 1024); } while (0)
; #define PG8_MMA(ai, bj, At, Bt) do { __builtin_amdgcn_s_setprio(1); _Pragma("unroll") for (int m = 0; m < 4; ++m) _Pragma("unroll") for (int n = 0; n < 2; ++n) _Pragma("unroll") for (int k = 0; k < 2; ++k) \
;         acc[ai][bj][m][n] = __builtin_amdgcn_mfma_f32_16x16x32_bf16(Bt[n][k], At[m][k], acc[ai][bj][m][n], 0, 0, 0); __builtin_amdgcn_s_setprio(0); } while (0)
; #define PG8_WAIT_V(n) asm volatile("s_waitcnt vmcnt(" #n ")" ::: "memory")
; #define PG8_WAIT_L(n) asm volatile("s_waitcnt lgkmcnt(" #n ")" ::: "memory")
; #define PG8_BAR __builtin_amdgcn_s_barrier()
; #define PG8_SCHED __builtin_amdgcn_sched_barrier(0)
; template <class Epi, class Sched, bool ALIGN_EPI = false, bool SP2 = false>
; __device__ __forceinline__ void gemm_phase(PG8_LAS unsigned char* lds, const Gemm g, const Sched& S, const Epi& E, int tid_in) {
;     ...
;             PG8_WAIT_V(8); PG8_WAIT_L(0); PG8_BAR; PG8_MMA(1, 0, At, B0); PG8_MMA(1, 1, At, B1); PG8_BAR; PG8_SCHED;
;             PG8_LDB(B0, 1, 0); PG8_LDB(B1, 1, 1); PG8_SCHED; PG8_LDA(At, 1, 0); PG8_STAGE(PG8_SA(0, 1), a2 + hstepA, voffA);
;             PG8_WAIT_V(8); PG8_WAIT_L(0); PG8_BAR; PG8_MMA(0, 0, At, B0); PG8_MMA(0, 1, At, B1); PG8_BAR; PG8_SCHED;
	s_setprio 1
	s_waitcnt lgkmcnt(0)
	v_mfma_f32_16x16x32_bf16 v[62:65], v[140:143], v[178:181], v[62:65]
	v_mfma_f32_16x16x32_bf16 v[58:61], v[154:157], v[178:181], v[58:61]
	v_mfma_f32_16x16x32_bf16 v[46:49], v[140:143], v[186:189], v[46:49]
	v_mfma_f32_16x16x32_bf16 v[42:45], v[154:157], v[186:189], v[42:45]
	v_mfma_f32_16x16x32_bf16 v[30:33], v[140:143], v[204:207], v[30:33]
	v_mfma_f32_16x16x32_bf16 v[26:29], v[154:157], v[204:207], v[26:29]
	v_mfma_f32_16x16x32_bf16 v[14:17], v[140:143], v[212:215], v[14:17]
	v_mfma_f32_16x16x32_bf16 v[10:13], v[154:157], v[212:215], v[10:13]
	v_mfma_f32_16x16x32_bf16 v[62:65], v[144:147], v[182:185], v[62:65]
	v_mfma_f32_16x16x32_bf16 v[58:61], v[158:161], v[182:185], v[58:61]
	v_mfma_f32_16x16x32_bf16 v[46:49], v[144:147], v[190:193], v[46:49]
	v_mfma_f32_16x16x32_bf16 v[42:45], v[158:161], v[190:193], v[42:45]
	v_mfma_f32_16x16x32_bf16 v[30:33], v[144:147], v[208:211], v[30:33]
	v_mfma_f32_16x16x32_bf16 v[26:29], v[158:161], v[208:211], v[26:29]
	v_mfma_f32_16x16x32_bf16 v[14:17], v[144:147], v[216:219], v[14:17]
	v_mfma_f32_16x16x32_bf16 v[10:13], v[158:161], v[216:219], v[10:13]
	v_mfma_f32_16x16x32_bf16 v[54:57], v[162:165], v[178:181], v[54:57]
	v_mfma_f32_16x16x32_bf16 v[50:53], v[170:173], v[178:181], v[50:53]
	v_mfma_f32_16x16x32_bf16 v[38:41], v[162:165], v[186:189], v[38:41]
	v_mfma_f32_16x16x32_bf16 v[34:37], v[170:173], v[186:189], v[34:37]
	v_mfma_f32_16x16x32_bf16 v[22:25], v[162:165], v[204:207], v[22:25]
	v_mfma_f32_16x16x32_bf16 v[18:21], v[170:173], v[204:207], v[18:21]
	v_mfma_f32_16x16x32_bf16 v[6:9], v[162:165], v[212:215], v[6:9]
	v_mfma_f32_16x16x32_bf16 v[2:5], v[170:173], v[212:215], v[2:5]
	v_mfma_f32_16x16x32_bf16 v[54:57], v[166:169], v[182:185], v[54:57]
	v_mfma_f32_16x16x32_bf16 v[50:53], v[174:177], v[182:185], v[50:53]
	v_mfma_f32_16x16x32_bf16 v[38:41], v[166:169], v[190:193], v[38:41]
	v_mfma_f32_16x16x32_bf16 v[34:37], v[174:177], v[190:193], v[34:37]
	v_mfma_f32_16x16x32_bf16 v[22:25], v[166:169], v[208:211], v[22:25]
	v_mfma_f32_16x16x32_bf16 v[18:21], v[174:177], v[208:211], v[18:21]
	v_mfma_f32_16x16x32_bf16 v[6:9], v[166:169], v[216:219], v[6:9]
	v_mfma_f32_16x16x32_bf16 v[2:5], v[174:177], v[216:219], v[2:5]
	s_setprio 0
	s_barrier
	s_add_i32 s15, 0, 0x18000
	s_add_i32 s58, 0, 0x1c000
	v_add_u32_e32 v158, s15, v151
	v_add_u32_e32 v174, s58, v151
	ds_read_b128 v[140:143], v158
	ds_read_b128 v[144:147], v158 offset:1024
	ds_read_b128 v[154:157], v158 offset:2048
	ds_read_b128 v[158:161], v158 offset:3072
	ds_read_b128 v[162:165], v174
	ds_read_b128 v[166:169], v174 offset:1024
	ds_read_b128 v[170:173], v174 offset:2048
	ds_read_b128 v[174:177], v174 offset:3072
	s_add_u32 s54, s54, s22
	s_addc_u32 s55, s55, s23
	s_mov_b32 m0, s64
	v_lshl_add_u64 v[228:229], s[54:55], 0, v[130:131]
	ds_read_b128 v[178:181], v153 offset:32768
	ds_read_b128 v[182:185], v153 offset:33792
	ds_read_b128 v[186:189], v153 offset:34816
	ds_read_b128 v[190:193], v153 offset:35840
	ds_read_b128 v[204:207], v153 offset:36864
	ds_read_b128 v[208:211], v153 offset:37888
	ds_read_b128 v[212:215], v153 offset:38912
	ds_read_b128 v[216:219], v153 offset:39936
	global_load_lds_dwordx4 v[228:229], off
	v_lshl_add_u64 v[228:229], s[54:55], 0, v[132:133]
	s_mov_b32 m0, s65
	s_nop 0
	global_load_lds_dwordx4 v[228:229], off
	s_waitcnt vmcnt(8)
	s_waitcnt lgkmcnt(0)
	s_barrier
	s_setprio 1
	s_waitcnt lgkmcnt(0)
	v_mfma_f32_16x16x32_bf16 v[126:129], v[140:143], v[178:181], v[126:129]
	v_mfma_f32_16x16x32_bf16 v[122:125], v[154:157], v[178:181], v[122:125]
	v_mfma_f32_16x16x32_bf16 v[110:113], v[140:143], v[186:189], v[110:113]
	v_mfma_f32_16x16x32_bf16 v[106:109], v[154:157], v[186:189], v[106:109]
	v_mfma_f32_16x16x32_bf16 v[94:97], v[140:143], v[204:207], v[94:97]
	v_mfma_f32_16x16x32_bf16 v[90:93], v[154:157], v[204:207], v[90:93]
	v_mfma_f32_16x16x32_bf16 v[78:81], v[140:143], v[212:215], v[78:81]
	v_mfma_f32_16x16x32_bf16 v[74:77], v[154:157], v[212:215], v[74:77]
	v_mfma_f32_16x16x32_bf16 v[126:129], v[144:147], v[182:185], v[126:129]
	v_mfma_f32_16x16x32_bf16 v[122:125], v[158:161], v[182:185], v[122:125]
	v_mfma_f32_16x16x32_bf16 v[110:113], v[144:147], v[190:193], v[110:113]
	v_mfma_f32_16x16x32_bf16 v[106:109], v[158:161], v[190:193], v[106:109]
	v_mfma_f32_16x16x32_bf16 v[94:97], v[144:147], v[208:211], v[94:97]
	v_mfma_f32_16x16x32_bf16 v[90:93], v[158:161], v[208:211], v[90:93]
	v_mfma_f32_16x16x32_bf16 v[78:81], v[144:147], v[216:219], v[78:81]
	v_mfma_f32_16x16x32_bf16 v[74:77], v[158:161], v[216:219], v[74:77]
	v_mfma_f32_16x16x32_bf16 v[118:121], v[162:165], v[178:181], v[118:121]
	v_mfma_f32_16x16x32_bf16 v[114:117], v[170:173], v[178:181], v[114:117]
	v_mfma_f32_16x16x32_bf16 v[102:105], v[162:165], v[186:189], v[102:105]
	v_mfma_f32_16x16x32_bf16 v[98:101], v[170:173], v[186:189], v[98:101]
	v_mfma_f32_16x16x32_bf16 v[86:89], v[162:165], v[204:207], v[86:89]
	v_mfma_f32_16x16x32_bf16 v[82:85], v[170:173], v[204:207], v[82:85]
	v_mfma_f32_16x16x32_bf16 v[70:73], v[162:165], v[212:215], v[70:73]
	v_mfma_f32_16x16x32_bf16 v[66:69], v[170:173], v[212:215], v[66:69]
	v_mfma_f32_16x16x32_bf16 v[118:121], v[166:169], v[182:185], v[118:121]
	v_mfma_f32_16x16x32_bf16 v[114:117], v[174:177], v[182:185], v[114:117]
	v_mfma_f32_16x16x32_bf16 v[102:105], v[166:169], v[190:193], v[102:105]
	v_mfma_f32_16x16x32_bf16 v[98:101], v[174:177], v[190:193], v[98:101]
	v_mfma_f32_16x16x32_bf16 v[86:89], v[166:169], v[208:211], v[86:89]
	v_mfma_f32_16x16x32_bf16 v[82:85], v[174:177], v[208:211], v[82:85]
	v_mfma_f32_16x16x32_bf16 v[70:73], v[166:169], v[216:219], v[70:73]
	v_mfma_f32_16x16x32_bf16 v[66:69], v[174:177], v[216:219], v[66:69]
	s_setprio 0
	s_barrier
; #define PG8_STAGE(bufoff, gbase, voff) do { _Pragma("unroll") for (int _i = 0; _i < 2; ++_i) \
;         __builtin_amdgcn_global_load_lds((const unsigned*)((const char*)(gbase) + (voff)[_i]), (PG8_LAS unsigned*)(lds + (bufoff) + ldsw + _i * 8192), 16, 0, 0); } while (0)
; #define PG8_LDA(dst, b, h) do { _Pragma("unroll") for (int m = 0; m < 4; ++m) _Pragma("unroll") for (int k = 0; k < 2; ++k) dst[m][k] = *(const PG8_LAS bf16x8*)(lds + PG8_SA(b, h) + aoff + m * 2048 + k * 1024); } while (0)
; #define PG8_MMA(ai, bj, At, Bt) do { __builtin_amdgcn_s_setprio(1); _Pragma("unroll") for (int m = 0; m < 4; ++m) _Pragma("unroll") for (int n = 0; n < 2; ++n) _Pragma("unroll") for (int k = 0; k < 2; ++k) \
;         acc[ai][bj][m][n] = __builtin_amdgcn_mfma_f32_16x16x32_bf16(Bt[n][k], At[m][k], acc[ai][bj][m][n], 0, 0, 0); __builtin_amdgcn_s_setprio(0); } while (0)
; #define PG8_WAIT_V(n) asm volatile("s_waitcnt vmcnt(" #n ")" ::: "memory")
; #define PG8_WAIT_L(n) asm volatile("s_waitcnt lgkmcnt(" #n ")" ::: "memory")
; #define PG8_BAR __builtin_amdgcn_s_barrier()
; #define PG8_SCHED __builtin_amdgcn_sched_barrier(0)
; template <class Epi, class Sched, bool ALIGN_EPI = false, bool SP2 = false>
; __device__ __forceinline__ void gemm_phase(PG8_LAS unsigned char* lds, const Gemm g, const Sched& S, const Epi& E, int tid_in) {
;     ...
;             PG8_LDA(At, 1, 1); PG8_STAGE(PG8_SB(1, 0), b3, voffB); PG8_STAGE(PG8_SB(1, 1), b3 + hstep, voffB); PG8_STAGE(PG8_SA(1, 0), a3, voffA);
;             PG8_WAIT_V(8); PG8_WAIT_L(0); PG8_BAR; PG8_MMA(1, 0, At, B0); PG8_MMA(1, 1, At, B1); PG8_BAR; PG8_SCHED;
	s_add_i32 s15, s15, s2
	v_lshl_add_u64 v[148:149], v[148:149], 0, s[28:29]
	s_mov_b32 m0, s15
	ds_read_b128 v[178:181], v153 offset:49152
	ds_read_b128 v[182:185], v153 offset:50176
	ds_read_b128 v[186:189], v153 offset:51200
	ds_read_b128 v[190:193], v153 offset:52224
	ds_read_b128 v[204:207], v153 offset:53248
	ds_read_b128 v[208:211], v153 offset:54272
	ds_read_b128 v[212:215], v153 offset:55296
	ds_read_b128 v[216:219], v153 offset:56320
	global_load_lds_dwordx4 v[148:149], off
	v_lshl_add_u64 v[148:149], v[194:195], 0, s[28:29]
	s_add_i32 m0, s15, 0x2000
	s_add_i32 s15, s58, s2
	global_load_lds_dwordx4 v[148:149], off
	v_lshl_add_u64 v[148:149], v[220:221], 0, s[28:29]
	s_mov_b32 m0, s15
	s_nop 0
	global_load_lds_dwordx4 v[148:149], off
	v_lshl_add_u64 v[148:149], v[222:223], 0, s[28:29]
	s_add_i32 m0, s15, 0x2000
	s_nop 0
	global_load_lds_dwordx4 v[148:149], off
	v_lshl_add_u64 v[148:149], v[224:225], 0, s[28:29]
	s_mov_b32 m0, s66
	s_nop 0
	global_load_lds_dwordx4 v[148:149], off
	v_lshl_add_u64 v[148:149], v[226:227], 0, s[28:29]
	s_mov_b32 m0, s67
	s_nop 0
	global_load_lds_dwordx4 v[148:149], off
	s_waitcnt vmcnt(8)
	s_waitcnt lgkmcnt(0)
	s_barrier
	s_setprio 1
	s_waitcnt lgkmcnt(0)
	v_mfma_f32_16x16x32_bf16 v[62:65], v[140:143], v[178:181], v[62:65]
	v_mfma_f32_16x16x32_bf16 v[58:61], v[154:157], v[178:181], v[58:61]
	v_mfma_f32_16x16x32_bf16 v[46:49], v[140:143], v[186:189], v[46:49]
	v_mfma_f32_16x16x32_bf16 v[42:45], v[154:157], v[186:189], v[42:45]
	v_mfma_f32_16x16x32_bf16 v[30:33], v[140:143], v[204:207], v[30:33]
	v_mfma_f32_16x16x32_bf16 v[26:29], v[154:157], v[204:207], v[26:29]
	v_mfma_f32_16x16x32_bf16 v[14:17], v[140:143], v[212:215], v[14:17]
	v_mfma_f32_16x16x32_bf16 v[10:13], v[154:157], v[212:215], v[10:13]
	v_mfma_f32_16x16x32_bf16 v[62:65], v[144:147], v[182:185], v[62:65]
	v_mfma_f32_16x16x32_bf16 v[58:61], v[158:161], v[182:185], v[58:61]
	v_mfma_f32_16x16x32_bf16 v[46:49], v[144:147], v[190:193], v[46:49]
	v_mfma_f32_16x16x32_bf16 v[42:45], v[158:161], v[190:193], v[42:45]
	v_mfma_f32_16x16x32_bf16 v[30:33], v[144:147], v[208:211], v[30:33]
	v_mfma_f32_16x16x32_bf16 v[26:29], v[158:161], v[208:211], v[26:29]
	v_mfma_f32_16x16x32_bf16 v[14:17], v[144:147], v[216:219], v[14:17]
	v_mfma_f32_16x16x32_bf16 v[10:13], v[158:161], v[216:219], v[10:13]
	v_mfma_f32_16x16x32_bf16 v[54:57], v[162:165], v[178:181], v[54:57]
	v_mfma_f32_16x16x32_bf16 v[50:53], v[170:173], v[178:181], v[50:53]
	v_mfma_f32_16x16x32_bf16 v[38:41], v[162:165], v[186:189], v[38:41]
	v_mfma_f32_16x16x32_bf16 v[34:37], v[170:173], v[186:189], v[34:37]
	v_mfma_f32_16x16x32_bf16 v[22:25], v[162:165], v[204:207], v[22:25]
	v_mfma_f32_16x16x32_bf16 v[18:21], v[170:173], v[204:207], v[18:21]
	v_mfma_f32_16x16x32_bf16 v[6:9], v[162:165], v[212:215], v[6:9]
	v_mfma_f32_16x16x32_bf16 v[2:5], v[170:173], v[212:215], v[2:5]
	v_mfma_f32_16x16x32_bf16 v[54:57], v[166:169], v[182:185], v[54:57]
	v_mfma_f32_16x16x32_bf16 v[50:53], v[174:177], v[182:185], v[50:53]
	v_mfma_f32_16x16x32_bf16 v[38:41], v[166:169], v[190:193], v[38:41]
	v_mfma_f32_16x16x32_bf16 v[34:37], v[174:177], v[190:193], v[34:37]
	v_mfma_f32_16x16x32_bf16 v[22:25], v[166:169], v[208:211], v[22:25]
	v_mfma_f32_16x16x32_bf16 v[18:21], v[174:177], v[208:211], v[18:21]
	v_mfma_f32_16x16x32_bf16 v[6:9], v[166:169], v[216:219], v[6:9]
	v_mfma_f32_16x16x32_bf16 v[2:5], v[174:177], v[216:219], v[2:5]
	s_setprio 0
	s_barrier
	s_add_u32 s52, s52, 0x100
	s_addc_u32 s53, s53, 0
	s_add_u32 s12, s12, 0x100
	s_addc_u32 s13, s13, 0
	s_cmp_ge_i32 s57, s69
	s_mov_b32 s15, s57
	s_cbranch_scc0 .LBB0_542
	s_movk_i32 s81, 0x4040

; #define PG8_STAGE(bufoff, gbase, voff) do { _Pragma("unroll") for (int _i = 0; _i < 2; ++_i) \
;         __builtin_amdgcn_global_load_lds((const unsigned*)((const char*)(gbase) + (voff)[_i]), (PG8_LAS unsigned*)(lds + (bufoff) + ldsw + _i * 8192), 16, 0, 0); } while (0)
; #define PG8_LDA(dst, b, h) do { _Pragma("unroll") for (int m = 0; m < 4; ++m) _Pragma("unroll") for (int k = 0; k < 2; ++k) dst[m][k] = *(const PG8_LAS bf16x8*)(lds + PG8_SA(b, h) + aoff + m * 2048 + k * 1024); } while (0)
; #define PG8_LDB(dst, b, h) do { _Pragma("unroll") for (int n = 0; n < 2; ++n) _Pragma("unroll") for (int k = 0; k < 2; ++k) dst[n][k] = *(const PG8_LAS bf16x8*)(lds + PG8_SB(b, h) + boff + n * 2048 + k * 1024); } while (0)
; #define PG8_MMA(ai, bj, At, Bt) do { __builtin_amdgcn_s_setprio(1); _Pragma("unroll") for (int m = 0; m < 4; ++m) _Pragma("unroll") for (int n = 0; n < 2; ++n) _Pragma("unroll") for (int k = 0; k < 2; ++k) \
;         acc[ai][bj][m][n] = __builtin_amdgcn_mfma_f32_16x16x32_bf16(Bt[n][k], At[m][k], acc[ai][bj][m][n], 0, 0, 0); __builtin_amdgcn_s_setprio(0); } while (0)
; #define PG8_WAIT_V(n) asm volatile("s_waitcnt vmcnt(" #n ")" ::: "memory")
; #define PG8_BAR __builtin_amdgcn_s_barrier()
; template <class Epi, class Sched, bool ALIGN_EPI = false, bool SP2 = false>
; __device__ __forceinline__ void gemm_phase(PG8_LAS unsigned char* lds, const Gemm g, const Sched& S, const Epi& E, int tid_in) {
;     ...
;         for (int t = 0; t < nt; t += 2) {
;             const bool last = (t == nt - 2);
;             const char* a1 = cA + (size_t)(t + 1) * kstep;
;             const char* a2 = last ? nA : cA + (size_t)(t + 2) * kstep; const char* b2 = last ? nB : cB + (size_t)(t + 2) * kstep;
;             const char* a3 = a2 + kstep; const char* b3 = b2 + kstep;
;             if (last && has_next) S.a_ready(nxt);
;             if constexpr (SP2) {
;             PG8_LDB(B0, 0, 0); PG8_LDB(B1, 0, 1); PG8_SCHED; PG8_LDA(At, 0, 0); PG8_STAGE(PG8_SA(1, 1), a1 + hstepA, voffA);
;             PG8_WAIT_V(8); PG8_WAIT_L(0); PG8_BAR; PG8_MMA(0, 0, At, B0); PG8_MMA(0, 1, At, B1); PG8_BAR; PG8_SCHED;
;             PG8_LDA(At, 0, 1); PG8_STAGE(PG8_SB(0, 0), b2, voffB); PG8_STAGE(PG8_SB(0, 1), b2 + hstep, voffB); PG8_STAGE(PG8_SA(0, 0), a2, voffA);
;             PG8_WAIT_V(8); PG8_WAIT_L(0); PG8_BAR; PG8_MMA(1, 0, At, B0); PG8_MMA(1, 1, At, B1); PG8_BAR; PG8_SCHED;
.LBB0_712:
	s_add_i32 s46, s15, 2
	s_add_u32 s40, s38, 0x80
	s_addc_u32 s41, s39, 0
	s_add_i32 s47, 0, 0x10000
	s_cmp_eq_u32 s59, s15
	s_cselect_b32 s41, s43, s41
	s_cselect_b32 s40, s42, s40
	v_add_u32_e32 v0, s47, v153
	s_cselect_b32 s65, s45, s13
	s_cselect_b32 s64, s44, s12
	s_add_i32 s15, 0, 0x14000
	ds_read_b128 v[142:145], v0
	ds_read_b128 v[146:149], v0 offset:1024
	ds_read_b128 v[160:163], v0 offset:2048
	ds_read_b128 v[164:167], v0 offset:3072
	v_add_u32_e32 v0, s15, v153
	ds_read_b128 v[168:171], v0
	ds_read_b128 v[172:175], v0 offset:1024
	ds_read_b128 v[176:179], v0 offset:2048
	ds_read_b128 v[180:183], v0 offset:3072
	v_lshl_add_u64 v[150:151], s[38:39], 0, v[138:139]
	s_add_i32 m0, s52, 0xc000
	ds_read_b128 v[184:187], v158
	ds_read_b128 v[188:191], v158 offset:1024
	ds_read_b128 v[192:195], v158 offset:2048
	ds_read_b128 v[204:207], v158 offset:3072
	ds_read_b128 v[208:211], v158 offset:4096
	ds_read_b128 v[212:215], v158 offset:5120
	ds_read_b128 v[216:219], v158 offset:6144
	ds_read_b128 v[220:223], v158 offset:7168
	global_load_lds_dwordx4 v[150:151], off
	v_lshl_add_u64 v[150:151], s[38:39], 0, v[140:141]
	s_add_i32 m0, s52, 0xe000
	s_nop 0
	global_load_lds_dwordx4 v[150:151], off
	s_waitcnt vmcnt(8)
	s_waitcnt lgkmcnt(0)
	s_barrier
	s_setprio 1
	s_waitcnt lgkmcnt(0)
	v_mfma_f32_16x16x32_bf16 v[122:125], v[142:145], v[184:187], v[122:125]
	v_mfma_f32_16x16x32_bf16 v[126:129], v[160:163], v[184:187], v[126:129]
	v_mfma_f32_16x16x32_bf16 v[110:113], v[142:145], v[192:195], v[110:113]
	v_mfma_f32_16x16x32_bf16 v[106:109], v[160:163], v[192:195], v[106:109]
	v_mfma_f32_16x16x32_bf16 v[94:97], v[142:145], v[208:211], v[94:97]
	v_mfma_f32_16x16x32_bf16 v[90:93], v[160:163], v[208:211], v[90:93]
	v_mfma_f32_16x16x32_bf16 v[78:81], v[142:145], v[216:219], v[78:81]
	v_mfma_f32_16x16x32_bf16 v[74:77], v[160:163], v[216:219], v[74:77]
	v_mfma_f32_16x16x32_bf16 v[122:125], v[146:149], v[188:191], v[122:125]
	v_mfma_f32_16x16x32_bf16 v[126:129], v[164:167], v[188:191], v[126:129]
	v_mfma_f32_16x16x32_bf16 v[110:113], v[146:149], v[204:207], v[110:113]
	v_mfma_f32_16x16x32_bf16 v[106:109], v[164:167], v[204:207], v[106:109]
	v_mfma_f32_16x16x32_bf16 v[94:97], v[146:149], v[212:215], v[94:97]
	v_mfma_f32_16x16x32_bf16 v[90:93], v[164:167], v[212:215], v[90:93]
	v_mfma_f32_16x16x32_bf16 v[78:81], v[146:149], v[220:223], v[78:81]
	v_mfma_f32_16x16x32_bf16 v[74:77], v[164:167], v[220:223], v[74:77]
	v_mfma_f32_16x16x32_bf16 v[118:121], v[168:171], v[184:187], v[118:121]
	v_mfma_f32_16x16x32_bf16 v[114:117], v[176:179], v[184:187], v[114:117]
	v_mfma_f32_16x16x32_bf16 v[102:105], v[168:171], v[192:195], v[102:105]
	v_mfma_f32_16x16x32_bf16 v[98:101], v[176:179], v[192:195], v[98:101]
	v_mfma_f32_16x16x32_bf16 v[86:89], v[168:171], v[208:211], v[86:89]
	v_mfma_f32_16x16x32_bf16 v[82:85], v[176:179], v[208:211], v[82:85]
	v_mfma_f32_16x16x32_bf16 v[70:73], v[168:171], v[216:219], v[70:73]
	v_mfma_f32_16x16x32_bf16 v[66:69], v[176:179], v[216:219], v[66:69]
	v_mfma_f32_16x16x32_bf16 v[118:121], v[172:175], v[188:191], v[118:121]
	v_mfma_f32_16x16x32_bf16 v[114:117], v[180:183], v[188:191], v[114:117]
	v_mfma_f32_16x16x32_bf16 v[102:105], v[172:175], v[204:207], v[102:105]
	v_mfma_f32_16x16x32_bf16 v[98:101], v[180:183], v[204:207], v[98:101]
	v_mfma_f32_16x16x32_bf16 v[86:89], v[172:175], v[212:215], v[86:89]
	v_mfma_f32_16x16x32_bf16 v[82:85], v[180:183], v[212:215], v[82:85]
	v_mfma_f32_16x16x32_bf16 v[70:73], v[172:175], v[220:223], v[70:73]
	v_mfma_f32_16x16x32_bf16 v[66:69], v[180:183], v[220:223], v[66:69]
	s_setprio 0
	s_barrier
	s_add_i32 s47, s47, s51
	v_lshl_add_u64 v[150:151], s[64:65], 0, v[132:133]
	s_mov_b32 m0, s47
	ds_read_b128 v[184:187], v158 offset:16384
	ds_read_b128 v[188:191], v158 offset:17408
	ds_read_b128 v[192:195], v158 offset:18432
	ds_read_b128 v[204:207], v158 offset:19456
	ds_read_b128 v[208:211], v158 offset:20480
	ds_read_b128 v[212:215], v158 offset:21504
	ds_read_b128 v[216:219], v158 offset:22528
	ds_read_b128 v[220:223], v158 offset:23552
	global_load_lds_dwordx4 v[150:151], off
	s_add_i32 m0, s47, 0x2000
	v_lshl_add_u64 v[224:225], s[64:65], 0, v[136:137]
	s_add_u32 s64, s64, s8
	s_addc_u32 s65, s65, s9
	s_add_i32 s15, s15, s51
	global_load_lds_dwordx4 v[224:225], off
	v_lshl_add_u64 v[226:227], s[64:65], 0, v[132:133]
	s_mov_b32 m0, s15
	v_lshl_add_u64 v[228:229], s[64:65], 0, v[136:137]
	global_load_lds_dwordx4 v[226:227], off
	s_add_i32 m0, s15, 0x2000
	v_lshl_add_u64 v[230:231], s[40:41], 0, v[130:131]
	global_load_lds_dwordx4 v[228:229], off
	s_mov_b32 m0, s52
	v_lshl_add_u64 v[232:233], s[40:41], 0, v[134:135]
	global_load_lds_dwordx4 v[230:231], off
	s_mov_b32 m0, s53
	s_nop 0
	global_load_lds_dwordx4 v[232:233], off
	s_waitcnt vmcnt(8)
	s_waitcnt lgkmcnt(0)
	s_barrier
; #define PG8_STAGE(bufoff, gbase, voff) do { _Pragma("unroll") for (int _i = 0; _i < 2; ++_i) \
;         __builtin_amdgcn_global_load_lds((const unsigned*)((const char*)(gbase) + (voff)[_i]), (PG8_LAS unsigned*)(lds + (bufoff) + ldsw + _i * 8192), 16, 0, 0); } while (0)
; #define PG8_LDA(dst, b, h) do { _Pragma("unroll") for (int m = 0; m < 4; ++m) _Pragma("unroll") for (int k = 0; k < 2; ++k) dst[m][k] = *(const PG8_LAS bf16x8*)(lds + PG8_SA(b, h) + aoff + m * 2048 + k * 1024); } while (0)
; #define PG8_LDB(dst, b, h) do { _Pragma("unroll") for (int n = 0; n < 2; ++n) _Pragma("unroll") for (int k = 0; k < 2; ++k) dst[n][k] = *(const PG8_LAS bf16x8*)(lds + PG8_SB(b, h) + boff + n * 2048 + k * 1024); } while (0)
; #define PG8_MMA(ai, bj, At, Bt) do { __builtin_amdgcn_s_setprio(1); _Pragma("unroll") for (int m = 0; m < 4; ++m) _Pragma("unroll") for (int n = 0; n < 2; ++n) _Pragma("unroll") for (int k = 0; k < 2; ++k) \
;         acc[ai][bj][m][n] = __builtin_amdgcn_mfma_f32_16x16x32_bf16(Bt[n][k], At[m][k], acc[ai][bj][m][n], 0, 0, 0); __builtin_amdgcn_s_setprio(0); } while (0)
; #define PG8_WAIT_V(n) asm volatile("s_waitcnt vmcnt(" #n ")" ::: "memory")
; #define PG8_WAIT_L(n) asm volatile("s_waitcnt lgkmcnt(" #n ")" ::: "memory")
; #define PG8_BAR __builtin_amdgcn_s_barrier()
; #define PG8_SCHED __builtin_amdgcn_sched_barrier(0)
; template <class Epi, class Sched, bool ALIGN_EPI = false, bool SP2 = false>
; __device__ __forceinline__ void gemm_phase(PG8_LAS unsigned char* lds, const Gemm g, const Sched& S, const Epi& E, int tid_in) {
;     ...
;             PG8_WAIT_V(8); PG8_WAIT_L(0); PG8_BAR; PG8_MMA(1, 0, At, B0); PG8_MMA(1, 1, At, B1); PG8_BAR; PG8_SCHED;
;             PG8_LDB(B0, 1, 0); PG8_LDB(B1, 1, 1); PG8_SCHED; PG8_LDA(At, 1, 0); PG8_STAGE(PG8_SA(0, 1), a2 + hstepA, voffA);
;             PG8_WAIT_V(8); PG8_WAIT_L(0); PG8_BAR; PG8_MMA(0, 0, At, B0); PG8_MMA(0, 1, At, B1); PG8_BAR; PG8_SCHED;
	s_setprio 1
	s_waitcnt lgkmcnt(0)
	v_mfma_f32_16x16x32_bf16 v[62:65], v[142:145], v[184:187], v[62:65]
	v_mfma_f32_16x16x32_bf16 v[58:61], v[160:163], v[184:187], v[58:61]
	v_mfma_f32_16x16x32_bf16 v[46:49], v[142:145], v[192:195], v[46:49]
	v_mfma_f32_16x16x32_bf16 v[42:45], v[160:163], v[192:195], v[42:45]
	v_mfma_f32_16x16x32_bf16 v[30:33], v[142:145], v[208:211], v[30:33]
	v_mfma_f32_16x16x32_bf16 v[26:29], v[160:163], v[208:211], v[26:29]
	v_mfma_f32_16x16x32_bf16 v[14:17], v[142:145], v[216:219], v[14:17]
	v_mfma_f32_16x16x32_bf16 v[10:13], v[160:163], v[216:219], v[10:13]
	v_mfma_f32_16x16x32_bf16 v[62:65], v[146:149], v[188:191], v[62:65]
	v_mfma_f32_16x16x32_bf16 v[58:61], v[164:167], v[188:191], v[58:61]
	v_mfma_f32_16x16x32_bf16 v[46:49], v[146:149], v[204:207], v[46:49]
	v_mfma_f32_16x16x32_bf16 v[42:45], v[164:167], v[204:207], v[42:45]
	v_mfma_f32_16x16x32_bf16 v[30:33], v[146:149], v[212:215], v[30:33]
	v_mfma_f32_16x16x32_bf16 v[26:29], v[164:167], v[212:215], v[26:29]
	v_mfma_f32_16x16x32_bf16 v[14:17], v[146:149], v[220:223], v[14:17]
	v_mfma_f32_16x16x32_bf16 v[10:13], v[164:167], v[220:223], v[10:13]
	v_mfma_f32_16x16x32_bf16 v[54:57], v[168:171], v[184:187], v[54:57]
	v_mfma_f32_16x16x32_bf16 v[50:53], v[176:179], v[184:187], v[50:53]
	v_mfma_f32_16x16x32_bf16 v[38:41], v[168:171], v[192:195], v[38:41]
	v_mfma_f32_16x16x32_bf16 v[34:37], v[176:179], v[192:195], v[34:37]
	v_mfma_f32_16x16x32_bf16 v[22:25], v[168:171], v[208:211], v[22:25]
	v_mfma_f32_16x16x32_bf16 v[18:21], v[176:179], v[208:211], v[18:21]
	v_mfma_f32_16x16x32_bf16 v[6:9], v[168:171], v[216:219], v[6:9]
	v_mfma_f32_16x16x32_bf16 v[2:5], v[176:179], v[216:219], v[2:5]
	v_mfma_f32_16x16x32_bf16 v[54:57], v[172:175], v[188:191], v[54:57]
	v_mfma_f32_16x16x32_bf16 v[50:53], v[180:183], v[188:191], v[50:53]
	v_mfma_f32_16x16x32_bf16 v[38:41], v[172:175], v[204:207], v[38:41]
	v_mfma_f32_16x16x32_bf16 v[34:37], v[180:183], v[204:207], v[34:37]
	v_mfma_f32_16x16x32_bf16 v[22:25], v[172:175], v[212:215], v[22:25]
	v_mfma_f32_16x16x32_bf16 v[18:21], v[180:183], v[212:215], v[18:21]
	v_mfma_f32_16x16x32_bf16 v[6:9], v[172:175], v[220:223], v[6:9]
	v_mfma_f32_16x16x32_bf16 v[2:5], v[180:183], v[220:223], v[2:5]
	s_setprio 0
	s_barrier
	s_add_i32 s15, 0, 0x18000
	v_add_u32_e32 v0, s15, v153
	s_add_i32 s47, 0, 0x1c000
	ds_read_b128 v[142:145], v0
	ds_read_b128 v[146:149], v0 offset:1024
	ds_read_b128 v[160:163], v0 offset:2048
	ds_read_b128 v[164:167], v0 offset:3072
	v_add_u32_e32 v0, s47, v153
	ds_read_b128 v[168:171], v0
	ds_read_b128 v[172:175], v0 offset:1024
	ds_read_b128 v[176:179], v0 offset:2048
	ds_read_b128 v[180:183], v0 offset:3072
	s_add_u32 s40, s40, s8
	s_addc_u32 s41, s41, s9
	s_mov_b32 m0, s54
	v_lshl_add_u64 v[234:235], s[40:41], 0, v[130:131]
	ds_read_b128 v[184:187], v158 offset:32768
	ds_read_b128 v[188:191], v158 offset:33792
	ds_read_b128 v[192:195], v158 offset:34816
	ds_read_b128 v[204:207], v158 offset:35840
	ds_read_b128 v[208:211], v158 offset:36864
	ds_read_b128 v[212:215], v158 offset:37888
	ds_read_b128 v[216:219], v158 offset:38912
	ds_read_b128 v[220:223], v158 offset:39936
	global_load_lds_dwordx4 v[234:235], off
	v_lshl_add_u64 v[234:235], s[40:41], 0, v[134:135]
	s_mov_b32 m0, s55
	s_nop 0
	global_load_lds_dwordx4 v[234:235], off
	s_waitcnt vmcnt(8)
	s_waitcnt lgkmcnt(0)
	s_barrier
	s_setprio 1
	s_waitcnt lgkmcnt(0)
	v_mfma_f32_16x16x32_bf16 v[122:125], v[142:145], v[184:187], v[122:125]
	v_mfma_f32_16x16x32_bf16 v[126:129], v[160:163], v[184:187], v[126:129]
	v_mfma_f32_16x16x32_bf16 v[110:113], v[142:145], v[192:195], v[110:113]
	v_mfma_f32_16x16x32_bf16 v[106:109], v[160:163], v[192:195], v[106:109]
	v_mfma_f32_16x16x32_bf16 v[94:97], v[142:145], v[208:211], v[94:97]
	v_mfma_f32_16x16x32_bf16 v[90:93], v[160:163], v[208:211], v[90:93]
	v_mfma_f32_16x16x32_bf16 v[78:81], v[142:145], v[216:219], v[78:81]
	v_mfma_f32_16x16x32_bf16 v[74:77], v[160:163], v[216:219], v[74:77]
	v_mfma_f32_16x16x32_bf16 v[122:125], v[146:149], v[188:191], v[122:125]
	v_mfma_f32_16x16x32_bf16 v[126:129], v[164:167], v[188:191], v[126:129]
	v_mfma_f32_16x16x32_bf16 v[110:113], v[146:149], v[204:207], v[110:113]
	v_mfma_f32_16x16x32_bf16 v[106:109], v[164:167], v[204:207], v[106:109]
	v_mfma_f32_16x16x32_bf16 v[94:97], v[146:149], v[212:215], v[94:97]
	v_mfma_f32_16x16x32_bf16 v[90:93], v[164:167], v[212:215], v[90:93]
	v_mfma_f32_16x16x32_bf16 v[78:81], v[146:149], v[220:223], v[78:81]
	v_mfma_f32_16x16x32_bf16 v[74:77], v[164:167], v[220:223], v[74:77]
	v_mfma_f32_16x16x32_bf16 v[118:121], v[168:171], v[184:187], v[118:121]
	v_mfma_f32_16x16x32_bf16 v[114:117], v[176:179], v[184:187], v[114:117]
	v_mfma_f32_16x16x32_bf16 v[102:105], v[168:171], v[192:195], v[102:105]
	v_mfma_f32_16x16x32_bf16 v[98:101], v[176:179], v[192:195], v[98:101]
	v_mfma_f32_16x16x32_bf16 v[86:89], v[168:171], v[208:211], v[86:89]
	v_mfma_f32_16x16x32_bf16 v[82:85], v[176:179], v[208:211], v[82:85]
	v_mfma_f32_16x16x32_bf16 v[70:73], v[168:171], v[216:219], v[70:73]
	v_mfma_f32_16x16x32_bf16 v[66:69], v[176:179], v[216:219], v[66:69]
	v_mfma_f32_16x16x32_bf16 v[118:121], v[172:175], v[188:191], v[118:121]
	v_mfma_f32_16x16x32_bf16 v[114:117], v[180:183], v[188:191], v[114:117]
	v_mfma_f32_16x16x32_bf16 v[102:105], v[172:175], v[204:207], v[102:105]
	v_mfma_f32_16x16x32_bf16 v[98:101], v[180:183], v[204:207], v[98:101]
	v_mfma_f32_16x16x32_bf16 v[86:89], v[172:175], v[212:215], v[86:89]
	v_mfma_f32_16x16x32_bf16 v[82:85], v[180:183], v[212:215], v[82:85]
	v_mfma_f32_16x16x32_bf16 v[70:73], v[172:175], v[220:223], v[70:73]
	v_mfma_f32_16x16x32_bf16 v[66:69], v[180:183], v[220:223], v[66:69]
	s_setprio 0
	s_barrier
; #define PG8_STAGE(bufoff, gbase, voff) do { _Pragma("unroll") for (int _i = 0; _i < 2; ++_i) \
;         __builtin_amdgcn_global_load_lds((const unsigned*)((const char*)(gbase) + (voff)[_i]), (PG8_LAS unsigned*)(lds + (bufoff) + ldsw + _i * 8192), 16, 0, 0); } while (0)
; #define PG8_LDA(dst, b, h) do { _Pragma("unroll") for (int m = 0; m < 4; ++m) _Pragma("unroll") for (int k = 0; k < 2; ++k) dst[m][k] = *(const PG8_LAS bf16x8*)(lds + PG8_SA(b, h) + aoff + m * 2048 + k * 1024); } while (0)
; #define PG8_MMA(ai, bj, At, Bt) do { __builtin_amdgcn_s_setprio(1); _Pragma("unroll") for (int m = 0; m < 4; ++m) _Pragma("unroll") for (int n = 0; n < 2; ++n) _Pragma("unroll") for (int k = 0; k < 2; ++k) \
;         acc[ai][bj][m][n] = __builtin_amdgcn_mfma_f32_16x16x32_bf16(Bt[n][k], At[m][k], acc[ai][bj][m][n], 0, 0, 0); __builtin_amdgcn_s_setprio(0); } while (0)
; #define PG8_WAIT_V(n) asm volatile("s_waitcnt vmcnt(" #n ")" ::: "memory")
; #define PG8_WAIT_L(n) asm volatile("s_waitcnt lgkmcnt(" #n ")" ::: "memory")
; #define PG8_BAR __builtin_amdgcn_s_barrier()
; #define PG8_SCHED __builtin_amdgcn_sched_barrier(0)
; template <class Epi, class Sched, bool ALIGN_EPI = false, bool SP2 = false>
; __device__ __forceinline__ void gemm_phase(PG8_LAS unsigned char* lds, const Gemm g, const Sched& S, const Epi& E, int tid_in) {
;     ...
;             PG8_LDA(At, 1, 1); PG8_STAGE(PG8_SB(1, 0), b3, voffB); PG8_STAGE(PG8_SB(1, 1), b3 + hstep, voffB); PG8_STAGE(PG8_SA(1, 0), a3, voffA);
;             PG8_WAIT_V(8); PG8_WAIT_L(0); PG8_BAR; PG8_MMA(1, 0, At, B0); PG8_MMA(1, 1, At, B1); PG8_BAR; PG8_SCHED;
	s_add_i32 s15, s15, s51
	v_lshl_add_u64 v[150:151], v[150:151], 0, s[28:29]
	s_mov_b32 m0, s15
	ds_read_b128 v[184:187], v158 offset:49152
	ds_read_b128 v[188:191], v158 offset:50176
	ds_read_b128 v[192:195], v158 offset:51200
	ds_read_b128 v[204:207], v158 offset:52224
	ds_read_b128 v[208:211], v158 offset:53248
	ds_read_b128 v[212:215], v158 offset:54272
	ds_read_b128 v[216:219], v158 offset:55296
	ds_read_b128 v[220:223], v158 offset:56320
	global_load_lds_dwordx4 v[150:151], off
	v_lshl_add_u64 v[150:151], v[224:225], 0, s[28:29]
	s_add_i32 m0, s15, 0x2000
	s_add_i32 s15, s47, s51
	global_load_lds_dwordx4 v[150:151], off
	v_lshl_add_u64 v[150:151], v[226:227], 0, s[28:29]
	s_mov_b32 m0, s15
	s_nop 0
	global_load_lds_dwordx4 v[150:151], off
	v_lshl_add_u64 v[150:151], v[228:229], 0, s[28:29]
	s_add_i32 m0, s15, 0x2000
	s_nop 0
	global_load_lds_dwordx4 v[150:151], off
	v_lshl_add_u64 v[150:151], v[230:231], 0, s[28:29]
	s_mov_b32 m0, s56
	s_nop 0
	global_load_lds_dwordx4 v[150:151], off
	v_lshl_add_u64 v[150:151], v[232:233], 0, s[28:29]
	s_mov_b32 m0, s57
	s_nop 0
	global_load_lds_dwordx4 v[150:151], off
	s_waitcnt vmcnt(8)
	s_waitcnt lgkmcnt(0)
	s_barrier
	s_setprio 1
	s_waitcnt lgkmcnt(0)
	v_mfma_f32_16x16x32_bf16 v[62:65], v[142:145], v[184:187], v[62:65]
	v_mfma_f32_16x16x32_bf16 v[58:61], v[160:163], v[184:187], v[58:61]
	v_mfma_f32_16x16x32_bf16 v[46:49], v[142:145], v[192:195], v[46:49]
	v_mfma_f32_16x16x32_bf16 v[42:45], v[160:163], v[192:195], v[42:45]
	v_mfma_f32_16x16x32_bf16 v[30:33], v[142:145], v[208:211], v[30:33]
	v_mfma_f32_16x16x32_bf16 v[26:29], v[160:163], v[208:211], v[26:29]
	v_mfma_f32_16x16x32_bf16 v[14:17], v[142:145], v[216:219], v[14:17]
	v_mfma_f32_16x16x32_bf16 v[10:13], v[160:163], v[216:219], v[10:13]
	v_mfma_f32_16x16x32_bf16 v[62:65], v[146:149], v[188:191], v[62:65]
	v_mfma_f32_16x16x32_bf16 v[58:61], v[164:167], v[188:191], v[58:61]
	v_mfma_f32_16x16x32_bf16 v[46:49], v[146:149], v[204:207], v[46:49]
	v_mfma_f32_16x16x32_bf16 v[42:45], v[164:167], v[204:207], v[42:45]
	v_mfma_f32_16x16x32_bf16 v[30:33], v[146:149], v[212:215], v[30:33]
	v_mfma_f32_16x16x32_bf16 v[26:29], v[164:167], v[212:215], v[26:29]
	v_mfma_f32_16x16x32_bf16 v[14:17], v[146:149], v[220:223], v[14:17]
	v_mfma_f32_16x16x32_bf16 v[10:13], v[164:167], v[220:223], v[10:13]
	v_mfma_f32_16x16x32_bf16 v[54:57], v[168:171], v[184:187], v[54:57]
	v_mfma_f32_16x16x32_bf16 v[50:53], v[176:179], v[184:187], v[50:53]
	v_mfma_f32_16x16x32_bf16 v[38:41], v[168:171], v[192:195], v[38:41]
	v_mfma_f32_16x16x32_bf16 v[34:37], v[176:179], v[192:195], v[34:37]
	v_mfma_f32_16x16x32_bf16 v[22:25], v[168:171], v[208:211], v[22:25]
	v_mfma_f32_16x16x32_bf16 v[18:21], v[176:179], v[208:211], v[18:21]
	v_mfma_f32_16x16x32_bf16 v[6:9], v[168:171], v[216:219], v[6:9]
	v_mfma_f32_16x16x32_bf16 v[2:5], v[176:179], v[216:219], v[2:5]
	v_mfma_f32_16x16x32_bf16 v[54:57], v[172:175], v[188:191], v[54:57]
	v_mfma_f32_16x16x32_bf16 v[50:53], v[180:183], v[188:191], v[50:53]
	v_mfma_f32_16x16x32_bf16 v[38:41], v[172:175], v[204:207], v[38:41]
	v_mfma_f32_16x16x32_bf16 v[34:37], v[180:183], v[204:207], v[34:37]
	v_mfma_f32_16x16x32_bf16 v[22:25], v[172:175], v[212:215], v[22:25]
	v_mfma_f32_16x16x32_bf16 v[18:21], v[180:183], v[212:215], v[18:21]
	v_mfma_f32_16x16x32_bf16 v[6:9], v[172:175], v[220:223], v[6:9]
	v_mfma_f32_16x16x32_bf16 v[2:5], v[180:183], v[220:223], v[2:5]
	s_setprio 0
	s_barrier
	s_add_u32 s38, s38, 0x100
	s_addc_u32 s39, s39, 0
	s_add_u32 s12, s12, 0x100
	s_addc_u32 s13, s13, 0
	s_cmp_ge_i32 s46, s58
	s_mov_b32 s15, s46
	s_cbranch_scc0 .LBB0_712
	s_movk_i32 s64, 0x6000
